# gMLP LayerNorm-statistics loop: 16 token rows loaded up front, wave reductions of 8 tokens interleaved (same op order); plus batched final norm
# speedup vs baseline: 1.0081x; 1.0081x over previous
; __device__ __forceinline__ float bf2f(unsigned h) { return __uint_as_float(h << 16); }
; __device__ __forceinline__ float gelu_(float x) { return x * sigm_(1.5957691216f * (x + 0.044715f * x * x * x)); }
; __device__ __forceinline__ float wave_sum(float v) {
; #pragma unroll
;     for (int o = 1; o < 64; o <<= 1) v += __shfl_xor(v, o);
;     return v;
; __device__ __forceinline__ void gmlp_mfma(LAS unsigned char* lds, const unsigned char* R, bf16_t* O, const float* lng, const float* lnb, const float* wsp, const float* bsp, int unit, int tid) {
;     ...
;     __syncthreads();
;     for (int i = 0; i < 16; ++i) { const int t = w * 16 + i; const u32x4 x4 = *(const u32x4*)(VV + (r0 + t) * AW + lane * 8);
;         float x[8]; x[0] = gelu_(bf2f(x4.x & 0xffff)); x[1] = gelu_(bf2f(x4.x >> 16)); x[2] = gelu_(bf2f(x4.y & 0xffff)); x[3] = gelu_(bf2f(x4.y >> 16)); x[4] = gelu_(bf2f(x4.z & 0xffff)); x[5] = gelu_(bf2f(x4.z >> 16)); x[6] = gelu_(bf2f(x4.w & 0xffff)); x[7] = gelu_(bf2f(x4.w >> 16));
;         float s = 0.f;
; #pragma unroll
;         for (int j = 0; j < 8; ++j) s += x[j];
;         const float mean = wave_sum(s) * (1.f / 512.f); float q = 0.f;
.LBB0_145:
	s_mov_b64 s[2:3], s[0:1]
	s_mov_b64 s[24:25], s[14:15]
	s_mov_b64 s[14:15], s[0:1]
	s_load_dwordx2 s[2:3], s[2:3], 0x48
	v_xor_b32_e32 v0, 1, v205
	s_load_dwordx2 s[28:29], s[14:15], 0x50
	s_mov_b64 s[14:15], s[0:1]
	v_cmp_lt_i32_e32 vcc, v0, v207
	v_xor_b32_e32 v8, 2, v205
	s_load_dwordx2 s[40:41], s[14:15], 0x58
	v_cndmask_b32_e32 v0, v205, v0, vcc
	v_cmp_lt_i32_e32 vcc, v8, v207
	s_mov_b64 s[14:15], s[0:1]
	v_readfirstlane_b32 s36, v176
	v_cndmask_b32_e32 v8, v205, v8, vcc
	v_lshlrev_b32_e32 v10, 2, v8
	v_xor_b32_e32 v8, 4, v205
	s_load_dwordx2 s[30:31], s[14:15], 0x60
	s_ashr_i32 s14, s36, 2
	v_cmp_lt_i32_e32 vcc, v8, v207
	s_lshr_b32 s17, s14, 4
	s_and_b32 s16, s14, -16
	v_cndmask_b32_e32 v8, v205, v8, vcc
	v_lshlrev_b32_e32 v11, 2, v8
	v_xor_b32_e32 v8, 8, v205
	s_lshl_b32 s14, s17, 6
	v_cmp_lt_i32_e32 vcc, v8, v207
	s_add_i32 s19, s14, 0
	s_ashr_i32 s15, s16, 31
	v_cndmask_b32_e32 v8, v205, v8, vcc
	v_cmp_lt_i32_e32 vcc, v206, v207
	s_add_u32 s14, s24, s16
	v_lshlrev_b32_e32 v12, 2, v8
	v_cndmask_b32_e32 v8, v205, v206, vcc
	v_cmp_lt_i32_e32 vcc, v208, v207
	v_writelane_b32 v252, s24, 53
	s_addc_u32 s15, s25, s15
	v_lshlrev_b32_e32 v13, 2, v8
	v_cndmask_b32_e32 v8, v205, v208, vcc
	s_lshl_b64 s[14:15], s[14:15], 10
	s_mov_b32 s18, 0
	v_lshlrev_b32_e32 v0, 2, v0
	v_lshlrev_b32_e32 v14, 2, v8
	v_lshl_add_u64 v[8:9], v[48:49], 0, s[14:15]
	s_waitcnt lgkmcnt(0)
	s_barrier
	v_writelane_b32 v252, s25, 54
	s_waitcnt lgkmcnt(0)
	s_mov_b64 s[14:15], 0x1000
	global_load_dwordx4 v[96:99], v[8:9], off
	global_load_dwordx4 v[100:103], v[8:9], off offset:1024
	global_load_dwordx4 v[104:107], v[8:9], off offset:2048
	global_load_dwordx4 v[108:111], v[8:9], off offset:3072
	v_lshl_add_u64 v[8:9], v[8:9], 0, s[14:15]
	global_load_dwordx4 v[112:115], v[8:9], off
	global_load_dwordx4 v[116:119], v[8:9], off offset:1024
	global_load_dwordx4 v[120:123], v[8:9], off offset:2048
	global_load_dwordx4 v[124:127], v[8:9], off offset:3072
	v_lshl_add_u64 v[8:9], v[8:9], 0, s[14:15]
	global_load_dwordx4 v[128:131], v[8:9], off
	global_load_dwordx4 v[132:135], v[8:9], off offset:1024
	global_load_dwordx4 v[136:139], v[8:9], off offset:2048
	global_load_dwordx4 v[140:143], v[8:9], off offset:3072
	v_lshl_add_u64 v[8:9], v[8:9], 0, s[14:15]
	global_load_dwordx4 v[144:147], v[8:9], off
	global_load_dwordx4 v[148:151], v[8:9], off offset:1024
	global_load_dwordx4 v[152:155], v[8:9], off offset:2048
	global_load_dwordx4 v[156:159], v[8:9], off offset:3072
	s_mov_b32 s24, 0x800000
	s_waitcnt vmcnt(15)
	v_lshlrev_b32_e32 v31, 16, v96
	v_and_b32_e32 v32, 0xffff0000, v96
	v_lshlrev_b32_e32 v160, 16, v97
	v_and_b32_e32 v161, 0xffff0000, v97
	v_lshlrev_b32_e32 v162, 16, v98
	v_and_b32_e32 v163, 0xffff0000, v98
	v_lshlrev_b32_e32 v199, 16, v99
	v_and_b32_e32 v200, 0xffff0000, v99
	v_mul_f32_e32 v210, 0x3d372713, v31
	v_mul_f32_e32 v211, 0x3d372713, v32
	v_mul_f32_e32 v212, 0x3d372713, v160
	v_mul_f32_e32 v213, 0x3d372713, v161
	v_mul_f32_e32 v214, 0x3d372713, v162
	v_mul_f32_e32 v215, 0x3d372713, v163
	v_mul_f32_e32 v216, 0x3d372713, v199
	v_mul_f32_e32 v217, 0x3d372713, v200
	v_mul_f32_e32 v210, v210, v31
	v_mul_f32_e32 v211, v211, v32
	v_mul_f32_e32 v212, v212, v160
	v_mul_f32_e32 v213, v213, v161
	v_mul_f32_e32 v214, v214, v162
	v_mul_f32_e32 v215, v215, v163
	v_mul_f32_e32 v216, v216, v199
	v_mul_f32_e32 v217, v217, v200
	v_fma_f32 v210, v210, v31, v31
	v_fma_f32 v211, v211, v32, v32
	v_fma_f32 v212, v212, v160, v160
	v_fma_f32 v213, v213, v161, v161
	v_fma_f32 v214, v214, v162, v162
	v_fma_f32 v215, v215, v163, v163
	v_fma_f32 v216, v216, v199, v199
	v_fma_f32 v217, v217, v200, v200
	v_mul_f32_e32 v210, 0x3fcc422a, v210
	v_mul_f32_e32 v211, 0x3fcc422a, v211
	v_mul_f32_e32 v212, 0x3fcc422a, v212
	v_mul_f32_e32 v213, 0x3fcc422a, v213
	v_mul_f32_e32 v214, 0x3fcc422a, v214
	v_mul_f32_e32 v215, 0x3fcc422a, v215
	v_mul_f32_e32 v216, 0x3fcc422a, v216
	v_mul_f32_e32 v217, 0x3fcc422a, v217
	v_mul_f32_e32 v210, 0xbfb8aa3b, v210
	v_mul_f32_e32 v211, 0xbfb8aa3b, v211
	v_mul_f32_e32 v212, 0xbfb8aa3b, v212
	v_mul_f32_e32 v213, 0xbfb8aa3b, v213
	v_mul_f32_e32 v214, 0xbfb8aa3b, v214
	v_mul_f32_e32 v215, 0xbfb8aa3b, v215
	v_mul_f32_e32 v216, 0xbfb8aa3b, v216
	v_mul_f32_e32 v217, 0xbfb8aa3b, v217
	v_exp_f32_e32 v210, v210
	v_exp_f32_e32 v211, v211
	v_exp_f32_e32 v212, v212
	v_exp_f32_e32 v213, v213
	v_exp_f32_e32 v214, v214
	v_exp_f32_e32 v215, v215
	v_exp_f32_e32 v216, v216
	v_exp_f32_e32 v217, v217
	v_add_f32_e32 v210, 1.0, v210
	v_add_f32_e32 v211, 1.0, v211
	v_add_f32_e32 v212, 1.0, v212
	v_add_f32_e32 v213, 1.0, v213
	v_add_f32_e32 v214, 1.0, v214
	v_add_f32_e32 v215, 1.0, v215
	v_add_f32_e32 v216, 1.0, v216
	v_add_f32_e32 v217, 1.0, v217
	v_rcp_f32_e32 v210, v210
	v_rcp_f32_e32 v211, v211
	v_rcp_f32_e32 v212, v212
	v_rcp_f32_e32 v213, v213
	v_rcp_f32_e32 v214, v214
	v_rcp_f32_e32 v215, v215
	v_rcp_f32_e32 v216, v216
	v_rcp_f32_e32 v217, v217
	v_fma_f32 v15, v210, v31, 0
	v_fmac_f32_e32 v15, v211, v32
	v_fmac_f32_e32 v15, v212, v160
	v_fmac_f32_e32 v15, v213, v161
	v_fmac_f32_e32 v15, v214, v162
	v_fmac_f32_e32 v15, v215, v163
	v_fmac_f32_e32 v15, v216, v199
	v_fmac_f32_e32 v15, v217, v200
	s_waitcnt vmcnt(14)
; __device__ __forceinline__ float bf2f(unsigned h) { return __uint_as_float(h << 16); }
; __device__ __forceinline__ float gelu_(float x) { return x * sigm_(1.5957691216f * (x + 0.044715f * x * x * x)); }
; __device__ __forceinline__ void gmlp_mfma(LAS unsigned char* lds, const unsigned char* R, bf16_t* O, const float* lng, const float* lnb, const float* wsp, const float* bsp, int unit, int tid) {
;     ...
;     for (int i = 0; i < 16; ++i) { const int t = w * 16 + i; const u32x4 x4 = *(const u32x4*)(VV + (r0 + t) * AW + lane * 8);
;         float x[8]; x[0] = gelu_(bf2f(x4.x & 0xffff)); x[1] = gelu_(bf2f(x4.x >> 16)); x[2] = gelu_(bf2f(x4.y & 0xffff)); x[3] = gelu_(bf2f(x4.y >> 16)); x[4] = gelu_(bf2f(x4.z & 0xffff)); x[5] = gelu_(bf2f(x4.z >> 16)); x[6] = gelu_(bf2f(x4.w & 0xffff)); x[7] = gelu_(bf2f(x4.w >> 16));
;         float s = 0.f;
; #pragma unroll
;         for (int j = 0; j < 8; ++j) s += x[j];
	v_lshlrev_b32_e32 v31, 16, v100
	v_and_b32_e32 v32, 0xffff0000, v100
	v_lshlrev_b32_e32 v160, 16, v101
	v_and_b32_e32 v161, 0xffff0000, v101
	v_lshlrev_b32_e32 v162, 16, v102
	v_and_b32_e32 v163, 0xffff0000, v102
	v_lshlrev_b32_e32 v199, 16, v103
	v_and_b32_e32 v200, 0xffff0000, v103
	v_mul_f32_e32 v218, 0x3d372713, v31
	v_mul_f32_e32 v219, 0x3d372713, v32
	v_mul_f32_e32 v220, 0x3d372713, v160
	v_mul_f32_e32 v221, 0x3d372713, v161
	v_mul_f32_e32 v222, 0x3d372713, v162
	v_mul_f32_e32 v223, 0x3d372713, v163
	v_mul_f32_e32 v224, 0x3d372713, v199
	v_mul_f32_e32 v225, 0x3d372713, v200
	v_mul_f32_e32 v218, v218, v31
	v_mul_f32_e32 v219, v219, v32
	v_mul_f32_e32 v220, v220, v160
	v_mul_f32_e32 v221, v221, v161
	v_mul_f32_e32 v222, v222, v162
	v_mul_f32_e32 v223, v223, v163
	v_mul_f32_e32 v224, v224, v199
	v_mul_f32_e32 v225, v225, v200
	v_fma_f32 v218, v218, v31, v31
	v_fma_f32 v219, v219, v32, v32
	v_fma_f32 v220, v220, v160, v160
	v_fma_f32 v221, v221, v161, v161
	v_fma_f32 v222, v222, v162, v162
	v_fma_f32 v223, v223, v163, v163
	v_fma_f32 v224, v224, v199, v199
	v_fma_f32 v225, v225, v200, v200
	v_mul_f32_e32 v218, 0x3fcc422a, v218
	v_mul_f32_e32 v219, 0x3fcc422a, v219
	v_mul_f32_e32 v220, 0x3fcc422a, v220
	v_mul_f32_e32 v221, 0x3fcc422a, v221
	v_mul_f32_e32 v222, 0x3fcc422a, v222
	v_mul_f32_e32 v223, 0x3fcc422a, v223
	v_mul_f32_e32 v224, 0x3fcc422a, v224
	v_mul_f32_e32 v225, 0x3fcc422a, v225
	v_mul_f32_e32 v218, 0xbfb8aa3b, v218
	v_mul_f32_e32 v219, 0xbfb8aa3b, v219
	v_mul_f32_e32 v220, 0xbfb8aa3b, v220
	v_mul_f32_e32 v221, 0xbfb8aa3b, v221
	v_mul_f32_e32 v222, 0xbfb8aa3b, v222
	v_mul_f32_e32 v223, 0xbfb8aa3b, v223
	v_mul_f32_e32 v224, 0xbfb8aa3b, v224
	v_mul_f32_e32 v225, 0xbfb8aa3b, v225
	v_exp_f32_e32 v218, v218
	v_exp_f32_e32 v219, v219
	v_exp_f32_e32 v220, v220
	v_exp_f32_e32 v221, v221
	v_exp_f32_e32 v222, v222
	v_exp_f32_e32 v223, v223
	v_exp_f32_e32 v224, v224
	v_exp_f32_e32 v225, v225
	v_add_f32_e32 v218, 1.0, v218
	v_add_f32_e32 v219, 1.0, v219
	v_add_f32_e32 v220, 1.0, v220
	v_add_f32_e32 v221, 1.0, v221
	v_add_f32_e32 v222, 1.0, v222
	v_add_f32_e32 v223, 1.0, v223
	v_add_f32_e32 v224, 1.0, v224
	v_add_f32_e32 v225, 1.0, v225
	v_rcp_f32_e32 v218, v218
	v_rcp_f32_e32 v219, v219
	v_rcp_f32_e32 v220, v220
	v_rcp_f32_e32 v221, v221
	v_rcp_f32_e32 v222, v222
	v_rcp_f32_e32 v223, v223
	v_rcp_f32_e32 v224, v224
	v_rcp_f32_e32 v225, v225
	v_fma_f32 v16, v218, v31, 0
	v_fmac_f32_e32 v16, v219, v32
	v_fmac_f32_e32 v16, v220, v160
	v_fmac_f32_e32 v16, v221, v161
	v_fmac_f32_e32 v16, v222, v162
	v_fmac_f32_e32 v16, v223, v163
	v_fmac_f32_e32 v16, v224, v199
	v_fmac_f32_e32 v16, v225, v200
	s_waitcnt vmcnt(13)
	v_lshlrev_b32_e32 v31, 16, v104
	v_and_b32_e32 v32, 0xffff0000, v104
	v_lshlrev_b32_e32 v160, 16, v105
	v_and_b32_e32 v161, 0xffff0000, v105
	v_lshlrev_b32_e32 v162, 16, v106
	v_and_b32_e32 v163, 0xffff0000, v106
	v_lshlrev_b32_e32 v199, 16, v107
	v_and_b32_e32 v200, 0xffff0000, v107
	v_mul_f32_e32 v226, 0x3d372713, v31
	v_mul_f32_e32 v227, 0x3d372713, v32
	v_mul_f32_e32 v228, 0x3d372713, v160
	v_mul_f32_e32 v229, 0x3d372713, v161
	v_mul_f32_e32 v230, 0x3d372713, v162
	v_mul_f32_e32 v231, 0x3d372713, v163
	v_mul_f32_e32 v232, 0x3d372713, v199
	v_mul_f32_e32 v233, 0x3d372713, v200
	v_mul_f32_e32 v226, v226, v31
	v_mul_f32_e32 v227, v227, v32
	v_mul_f32_e32 v228, v228, v160
	v_mul_f32_e32 v229, v229, v161
	v_mul_f32_e32 v230, v230, v162
	v_mul_f32_e32 v231, v231, v163
	v_mul_f32_e32 v232, v232, v199
	v_mul_f32_e32 v233, v233, v200
	v_fma_f32 v226, v226, v31, v31
	v_fma_f32 v227, v227, v32, v32
	v_fma_f32 v228, v228, v160, v160
	v_fma_f32 v229, v229, v161, v161
	v_fma_f32 v230, v230, v162, v162
	v_fma_f32 v231, v231, v163, v163
	v_fma_f32 v232, v232, v199, v199
	v_fma_f32 v233, v233, v200, v200
	v_mul_f32_e32 v226, 0x3fcc422a, v226
	v_mul_f32_e32 v227, 0x3fcc422a, v227
	v_mul_f32_e32 v228, 0x3fcc422a, v228
	v_mul_f32_e32 v229, 0x3fcc422a, v229
	v_mul_f32_e32 v230, 0x3fcc422a, v230
	v_mul_f32_e32 v231, 0x3fcc422a, v231
	v_mul_f32_e32 v232, 0x3fcc422a, v232
	v_mul_f32_e32 v233, 0x3fcc422a, v233
	v_mul_f32_e32 v226, 0xbfb8aa3b, v226
	v_mul_f32_e32 v227, 0xbfb8aa3b, v227
	v_mul_f32_e32 v228, 0xbfb8aa3b, v228
	v_mul_f32_e32 v229, 0xbfb8aa3b, v229
	v_mul_f32_e32 v230, 0xbfb8aa3b, v230
	v_mul_f32_e32 v231, 0xbfb8aa3b, v231
	v_mul_f32_e32 v232, 0xbfb8aa3b, v232
	v_mul_f32_e32 v233, 0xbfb8aa3b, v233
	v_exp_f32_e32 v226, v226
	v_exp_f32_e32 v227, v227
	v_exp_f32_e32 v228, v228
	v_exp_f32_e32 v229, v229
	v_exp_f32_e32 v230, v230
	v_exp_f32_e32 v231, v231
	v_exp_f32_e32 v232, v232
	v_exp_f32_e32 v233, v233
	v_add_f32_e32 v226, 1.0, v226
	v_add_f32_e32 v227, 1.0, v227
	v_add_f32_e32 v228, 1.0, v228
	v_add_f32_e32 v229, 1.0, v229
	v_add_f32_e32 v230, 1.0, v230
	v_add_f32_e32 v231, 1.0, v231
	v_add_f32_e32 v232, 1.0, v232
	v_add_f32_e32 v233, 1.0, v233
	v_rcp_f32_e32 v226, v226
	v_rcp_f32_e32 v227, v227
	v_rcp_f32_e32 v228, v228
	v_rcp_f32_e32 v229, v229
	v_rcp_f32_e32 v230, v230
	v_rcp_f32_e32 v231, v231
	v_rcp_f32_e32 v232, v232
	v_rcp_f32_e32 v233, v233
	v_fma_f32 v17, v226, v31, 0
	v_fmac_f32_e32 v17, v227, v32
	v_fmac_f32_e32 v17, v228, v160
	v_fmac_f32_e32 v17, v229, v161
	v_fmac_f32_e32 v17, v230, v162
	v_fmac_f32_e32 v17, v231, v163
	v_fmac_f32_e32 v17, v232, v199
	v_fmac_f32_e32 v17, v233, v200
	s_waitcnt vmcnt(12)
; __device__ __forceinline__ float bf2f(unsigned h) { return __uint_as_float(h << 16); }
; __device__ __forceinline__ float gelu_(float x) { return x * sigm_(1.5957691216f * (x + 0.044715f * x * x * x)); }
; __device__ __forceinline__ void gmlp_mfma(LAS unsigned char* lds, const unsigned char* R, bf16_t* O, const float* lng, const float* lnb, const float* wsp, const float* bsp, int unit, int tid) {
;     ...
;     for (int i = 0; i < 16; ++i) { const int t = w * 16 + i; const u32x4 x4 = *(const u32x4*)(VV + (r0 + t) * AW + lane * 8);
;         float x[8]; x[0] = gelu_(bf2f(x4.x & 0xffff)); x[1] = gelu_(bf2f(x4.x >> 16)); x[2] = gelu_(bf2f(x4.y & 0xffff)); x[3] = gelu_(bf2f(x4.y >> 16)); x[4] = gelu_(bf2f(x4.z & 0xffff)); x[5] = gelu_(bf2f(x4.z >> 16)); x[6] = gelu_(bf2f(x4.w & 0xffff)); x[7] = gelu_(bf2f(x4.w >> 16));
;         float s = 0.f;
; #pragma unroll
;         for (int j = 0; j < 8; ++j) s += x[j];
	v_lshlrev_b32_e32 v31, 16, v108
	v_and_b32_e32 v32, 0xffff0000, v108
	v_lshlrev_b32_e32 v160, 16, v109
	v_and_b32_e32 v161, 0xffff0000, v109
	v_lshlrev_b32_e32 v162, 16, v110
	v_and_b32_e32 v163, 0xffff0000, v110
	v_lshlrev_b32_e32 v199, 16, v111
	v_and_b32_e32 v200, 0xffff0000, v111
	v_mul_f32_e32 v234, 0x3d372713, v31
	v_mul_f32_e32 v235, 0x3d372713, v32
	v_mul_f32_e32 v236, 0x3d372713, v160
	v_mul_f32_e32 v237, 0x3d372713, v161
	v_mul_f32_e32 v238, 0x3d372713, v162
	v_mul_f32_e32 v239, 0x3d372713, v163
	v_mul_f32_e32 v240, 0x3d372713, v199
	v_mul_f32_e32 v241, 0x3d372713, v200
	v_mul_f32_e32 v234, v234, v31
	v_mul_f32_e32 v235, v235, v32
	v_mul_f32_e32 v236, v236, v160
	v_mul_f32_e32 v237, v237, v161
	v_mul_f32_e32 v238, v238, v162
	v_mul_f32_e32 v239, v239, v163
	v_mul_f32_e32 v240, v240, v199
	v_mul_f32_e32 v241, v241, v200
	v_fma_f32 v234, v234, v31, v31
	v_fma_f32 v235, v235, v32, v32
	v_fma_f32 v236, v236, v160, v160
	v_fma_f32 v237, v237, v161, v161
	v_fma_f32 v238, v238, v162, v162
	v_fma_f32 v239, v239, v163, v163
	v_fma_f32 v240, v240, v199, v199
	v_fma_f32 v241, v241, v200, v200
	v_mul_f32_e32 v234, 0x3fcc422a, v234
	v_mul_f32_e32 v235, 0x3fcc422a, v235
	v_mul_f32_e32 v236, 0x3fcc422a, v236
	v_mul_f32_e32 v237, 0x3fcc422a, v237
	v_mul_f32_e32 v238, 0x3fcc422a, v238
	v_mul_f32_e32 v239, 0x3fcc422a, v239
	v_mul_f32_e32 v240, 0x3fcc422a, v240
	v_mul_f32_e32 v241, 0x3fcc422a, v241
	v_mul_f32_e32 v234, 0xbfb8aa3b, v234
	v_mul_f32_e32 v235, 0xbfb8aa3b, v235
	v_mul_f32_e32 v236, 0xbfb8aa3b, v236
	v_mul_f32_e32 v237, 0xbfb8aa3b, v237
	v_mul_f32_e32 v238, 0xbfb8aa3b, v238
	v_mul_f32_e32 v239, 0xbfb8aa3b, v239
	v_mul_f32_e32 v240, 0xbfb8aa3b, v240
	v_mul_f32_e32 v241, 0xbfb8aa3b, v241
	v_exp_f32_e32 v234, v234
	v_exp_f32_e32 v235, v235
	v_exp_f32_e32 v236, v236
	v_exp_f32_e32 v237, v237
	v_exp_f32_e32 v238, v238
	v_exp_f32_e32 v239, v239
	v_exp_f32_e32 v240, v240
	v_exp_f32_e32 v241, v241
	v_add_f32_e32 v234, 1.0, v234
	v_add_f32_e32 v235, 1.0, v235
	v_add_f32_e32 v236, 1.0, v236
	v_add_f32_e32 v237, 1.0, v237
	v_add_f32_e32 v238, 1.0, v238
	v_add_f32_e32 v239, 1.0, v239
	v_add_f32_e32 v240, 1.0, v240
	v_add_f32_e32 v241, 1.0, v241
	v_rcp_f32_e32 v234, v234
	v_rcp_f32_e32 v235, v235
	v_rcp_f32_e32 v236, v236
	v_rcp_f32_e32 v237, v237
	v_rcp_f32_e32 v238, v238
	v_rcp_f32_e32 v239, v239
	v_rcp_f32_e32 v240, v240
	v_rcp_f32_e32 v241, v241
	v_fma_f32 v18, v234, v31, 0
	v_fmac_f32_e32 v18, v235, v32
	v_fmac_f32_e32 v18, v236, v160
	v_fmac_f32_e32 v18, v237, v161
	v_fmac_f32_e32 v18, v238, v162
	v_fmac_f32_e32 v18, v239, v163
	v_fmac_f32_e32 v18, v240, v199
	v_fmac_f32_e32 v18, v241, v200
	s_waitcnt vmcnt(11)
	v_lshlrev_b32_e32 v31, 16, v112
	v_and_b32_e32 v32, 0xffff0000, v112
	v_lshlrev_b32_e32 v160, 16, v113
	v_and_b32_e32 v161, 0xffff0000, v113
	v_lshlrev_b32_e32 v162, 16, v114
	v_and_b32_e32 v163, 0xffff0000, v114
	v_lshlrev_b32_e32 v199, 16, v115
	v_and_b32_e32 v200, 0xffff0000, v115
	v_mul_f32_e32 v242, 0x3d372713, v31
	v_mul_f32_e32 v243, 0x3d372713, v32
	v_mul_f32_e32 v244, 0x3d372713, v160
	v_mul_f32_e32 v245, 0x3d372713, v161
	v_mul_f32_e32 v246, 0x3d372713, v162
	v_mul_f32_e32 v247, 0x3d372713, v163
	v_mul_f32_e32 v248, 0x3d372713, v199
	v_mul_f32_e32 v249, 0x3d372713, v200
	v_mul_f32_e32 v242, v242, v31
	v_mul_f32_e32 v243, v243, v32
	v_mul_f32_e32 v244, v244, v160
	v_mul_f32_e32 v245, v245, v161
	v_mul_f32_e32 v246, v246, v162
	v_mul_f32_e32 v247, v247, v163
	v_mul_f32_e32 v248, v248, v199
	v_mul_f32_e32 v249, v249, v200
	v_fma_f32 v242, v242, v31, v31
	v_fma_f32 v243, v243, v32, v32
	v_fma_f32 v244, v244, v160, v160
	v_fma_f32 v245, v245, v161, v161
	v_fma_f32 v246, v246, v162, v162
	v_fma_f32 v247, v247, v163, v163
	v_fma_f32 v248, v248, v199, v199
	v_fma_f32 v249, v249, v200, v200
	v_mul_f32_e32 v242, 0x3fcc422a, v242
	v_mul_f32_e32 v243, 0x3fcc422a, v243
	v_mul_f32_e32 v244, 0x3fcc422a, v244
	v_mul_f32_e32 v245, 0x3fcc422a, v245
	v_mul_f32_e32 v246, 0x3fcc422a, v246
	v_mul_f32_e32 v247, 0x3fcc422a, v247
	v_mul_f32_e32 v248, 0x3fcc422a, v248
	v_mul_f32_e32 v249, 0x3fcc422a, v249
	v_mul_f32_e32 v242, 0xbfb8aa3b, v242
	v_mul_f32_e32 v243, 0xbfb8aa3b, v243
	v_mul_f32_e32 v244, 0xbfb8aa3b, v244
	v_mul_f32_e32 v245, 0xbfb8aa3b, v245
	v_mul_f32_e32 v246, 0xbfb8aa3b, v246
	v_mul_f32_e32 v247, 0xbfb8aa3b, v247
	v_mul_f32_e32 v248, 0xbfb8aa3b, v248
	v_mul_f32_e32 v249, 0xbfb8aa3b, v249
	v_exp_f32_e32 v242, v242
	v_exp_f32_e32 v243, v243
	v_exp_f32_e32 v244, v244
	v_exp_f32_e32 v245, v245
	v_exp_f32_e32 v246, v246
	v_exp_f32_e32 v247, v247
	v_exp_f32_e32 v248, v248
	v_exp_f32_e32 v249, v249
	v_add_f32_e32 v242, 1.0, v242
	v_add_f32_e32 v243, 1.0, v243
	v_add_f32_e32 v244, 1.0, v244
	v_add_f32_e32 v245, 1.0, v245
	v_add_f32_e32 v246, 1.0, v246
	v_add_f32_e32 v247, 1.0, v247
	v_add_f32_e32 v248, 1.0, v248
	v_add_f32_e32 v249, 1.0, v249
	v_rcp_f32_e32 v242, v242
	v_rcp_f32_e32 v243, v243
	v_rcp_f32_e32 v244, v244
	v_rcp_f32_e32 v245, v245
	v_rcp_f32_e32 v246, v246
	v_rcp_f32_e32 v247, v247
	v_rcp_f32_e32 v248, v248
	v_rcp_f32_e32 v249, v249
	v_fma_f32 v19, v242, v31, 0
	v_fmac_f32_e32 v19, v243, v32
	v_fmac_f32_e32 v19, v244, v160
	v_fmac_f32_e32 v19, v245, v161
	v_fmac_f32_e32 v19, v246, v162
	v_fmac_f32_e32 v19, v247, v163
	v_fmac_f32_e32 v19, v248, v199
	v_fmac_f32_e32 v19, v249, v200
	s_waitcnt vmcnt(10)
; __device__ __forceinline__ float bf2f(unsigned h) { return __uint_as_float(h << 16); }
; __device__ __forceinline__ float gelu_(float x) { return x * sigm_(1.5957691216f * (x + 0.044715f * x * x * x)); }
; __device__ __forceinline__ void gmlp_mfma(LAS unsigned char* lds, const unsigned char* R, bf16_t* O, const float* lng, const float* lnb, const float* wsp, const float* bsp, int unit, int tid) {
;     ...
;     for (int i = 0; i < 16; ++i) { const int t = w * 16 + i; const u32x4 x4 = *(const u32x4*)(VV + (r0 + t) * AW + lane * 8);
;         float x[8]; x[0] = gelu_(bf2f(x4.x & 0xffff)); x[1] = gelu_(bf2f(x4.x >> 16)); x[2] = gelu_(bf2f(x4.y & 0xffff)); x[3] = gelu_(bf2f(x4.y >> 16)); x[4] = gelu_(bf2f(x4.z & 0xffff)); x[5] = gelu_(bf2f(x4.z >> 16)); x[6] = gelu_(bf2f(x4.w & 0xffff)); x[7] = gelu_(bf2f(x4.w >> 16));
;         float s = 0.f;
; #pragma unroll
;         for (int j = 0; j < 8; ++j) s += x[j];
	v_lshlrev_b32_e32 v31, 16, v116
	v_and_b32_e32 v32, 0xffff0000, v116
	v_lshlrev_b32_e32 v160, 16, v117
	v_and_b32_e32 v161, 0xffff0000, v117
	v_lshlrev_b32_e32 v162, 16, v118
	v_and_b32_e32 v163, 0xffff0000, v118
	v_lshlrev_b32_e32 v199, 16, v119
	v_and_b32_e32 v200, 0xffff0000, v119
	v_mul_f32_e32 v250, 0x3d372713, v31
	v_mul_f32_e32 v251, 0x3d372713, v32
	v_mul_f32_e32 v177, 0x3d372713, v160
	v_mul_f32_e32 v178, 0x3d372713, v161
	v_mul_f32_e32 v179, 0x3d372713, v162
	v_mul_f32_e32 v180, 0x3d372713, v163
	v_mul_f32_e32 v181, 0x3d372713, v199
	v_mul_f32_e32 v182, 0x3d372713, v200
	v_mul_f32_e32 v250, v250, v31
	v_mul_f32_e32 v251, v251, v32
	v_mul_f32_e32 v177, v177, v160
	v_mul_f32_e32 v178, v178, v161
	v_mul_f32_e32 v179, v179, v162
	v_mul_f32_e32 v180, v180, v163
	v_mul_f32_e32 v181, v181, v199
	v_mul_f32_e32 v182, v182, v200
	v_fma_f32 v250, v250, v31, v31
	v_fma_f32 v251, v251, v32, v32
	v_fma_f32 v177, v177, v160, v160
	v_fma_f32 v178, v178, v161, v161
	v_fma_f32 v179, v179, v162, v162
	v_fma_f32 v180, v180, v163, v163
	v_fma_f32 v181, v181, v199, v199
	v_fma_f32 v182, v182, v200, v200
	v_mul_f32_e32 v250, 0x3fcc422a, v250
	v_mul_f32_e32 v251, 0x3fcc422a, v251
	v_mul_f32_e32 v177, 0x3fcc422a, v177
	v_mul_f32_e32 v178, 0x3fcc422a, v178
	v_mul_f32_e32 v179, 0x3fcc422a, v179
	v_mul_f32_e32 v180, 0x3fcc422a, v180
	v_mul_f32_e32 v181, 0x3fcc422a, v181
	v_mul_f32_e32 v182, 0x3fcc422a, v182
	v_mul_f32_e32 v250, 0xbfb8aa3b, v250
	v_mul_f32_e32 v251, 0xbfb8aa3b, v251
	v_mul_f32_e32 v177, 0xbfb8aa3b, v177
	v_mul_f32_e32 v178, 0xbfb8aa3b, v178
	v_mul_f32_e32 v179, 0xbfb8aa3b, v179
	v_mul_f32_e32 v180, 0xbfb8aa3b, v180
	v_mul_f32_e32 v181, 0xbfb8aa3b, v181
	v_mul_f32_e32 v182, 0xbfb8aa3b, v182
	v_exp_f32_e32 v250, v250
	v_exp_f32_e32 v251, v251
	v_exp_f32_e32 v177, v177
	v_exp_f32_e32 v178, v178
	v_exp_f32_e32 v179, v179
	v_exp_f32_e32 v180, v180
	v_exp_f32_e32 v181, v181
	v_exp_f32_e32 v182, v182
	v_add_f32_e32 v250, 1.0, v250
	v_add_f32_e32 v251, 1.0, v251
	v_add_f32_e32 v177, 1.0, v177
	v_add_f32_e32 v178, 1.0, v178
	v_add_f32_e32 v179, 1.0, v179
	v_add_f32_e32 v180, 1.0, v180
	v_add_f32_e32 v181, 1.0, v181
	v_add_f32_e32 v182, 1.0, v182
	v_rcp_f32_e32 v250, v250
	v_rcp_f32_e32 v251, v251
	v_rcp_f32_e32 v177, v177
	v_rcp_f32_e32 v178, v178
	v_rcp_f32_e32 v179, v179
	v_rcp_f32_e32 v180, v180
	v_rcp_f32_e32 v181, v181
	v_rcp_f32_e32 v182, v182
	v_fma_f32 v20, v250, v31, 0
	v_fmac_f32_e32 v20, v251, v32
	v_fmac_f32_e32 v20, v177, v160
	v_fmac_f32_e32 v20, v178, v161
	v_fmac_f32_e32 v20, v179, v162
	v_fmac_f32_e32 v20, v180, v163
	v_fmac_f32_e32 v20, v181, v199
	v_fmac_f32_e32 v20, v182, v200
	s_waitcnt vmcnt(9)
	v_lshlrev_b32_e32 v31, 16, v120
	v_and_b32_e32 v32, 0xffff0000, v120
	v_lshlrev_b32_e32 v160, 16, v121
	v_and_b32_e32 v161, 0xffff0000, v121
	v_lshlrev_b32_e32 v162, 16, v122
	v_and_b32_e32 v163, 0xffff0000, v122
	v_lshlrev_b32_e32 v199, 16, v123
	v_and_b32_e32 v200, 0xffff0000, v123
	v_mul_f32_e32 v183, 0x3d372713, v31
	v_mul_f32_e32 v184, 0x3d372713, v32
	v_mul_f32_e32 v185, 0x3d372713, v160
	v_mul_f32_e32 v186, 0x3d372713, v161
	v_mul_f32_e32 v187, 0x3d372713, v162
	v_mul_f32_e32 v188, 0x3d372713, v163
	v_mul_f32_e32 v189, 0x3d372713, v199
	v_mul_f32_e32 v190, 0x3d372713, v200
	v_mul_f32_e32 v183, v183, v31
	v_mul_f32_e32 v184, v184, v32
	v_mul_f32_e32 v185, v185, v160
	v_mul_f32_e32 v186, v186, v161
	v_mul_f32_e32 v187, v187, v162
	v_mul_f32_e32 v188, v188, v163
	v_mul_f32_e32 v189, v189, v199
	v_mul_f32_e32 v190, v190, v200
	v_fma_f32 v183, v183, v31, v31
	v_fma_f32 v184, v184, v32, v32
	v_fma_f32 v185, v185, v160, v160
	v_fma_f32 v186, v186, v161, v161
	v_fma_f32 v187, v187, v162, v162
	v_fma_f32 v188, v188, v163, v163
	v_fma_f32 v189, v189, v199, v199
	v_fma_f32 v190, v190, v200, v200
	v_mul_f32_e32 v183, 0x3fcc422a, v183
	v_mul_f32_e32 v184, 0x3fcc422a, v184
	v_mul_f32_e32 v185, 0x3fcc422a, v185
	v_mul_f32_e32 v186, 0x3fcc422a, v186
	v_mul_f32_e32 v187, 0x3fcc422a, v187
	v_mul_f32_e32 v188, 0x3fcc422a, v188
	v_mul_f32_e32 v189, 0x3fcc422a, v189
	v_mul_f32_e32 v190, 0x3fcc422a, v190
	v_mul_f32_e32 v183, 0xbfb8aa3b, v183
	v_mul_f32_e32 v184, 0xbfb8aa3b, v184
	v_mul_f32_e32 v185, 0xbfb8aa3b, v185
	v_mul_f32_e32 v186, 0xbfb8aa3b, v186
	v_mul_f32_e32 v187, 0xbfb8aa3b, v187
	v_mul_f32_e32 v188, 0xbfb8aa3b, v188
	v_mul_f32_e32 v189, 0xbfb8aa3b, v189
	v_mul_f32_e32 v190, 0xbfb8aa3b, v190
	v_exp_f32_e32 v183, v183
	v_exp_f32_e32 v184, v184
	v_exp_f32_e32 v185, v185
	v_exp_f32_e32 v186, v186
	v_exp_f32_e32 v187, v187
	v_exp_f32_e32 v188, v188
	v_exp_f32_e32 v189, v189
	v_exp_f32_e32 v190, v190
	v_add_f32_e32 v183, 1.0, v183
	v_add_f32_e32 v184, 1.0, v184
	v_add_f32_e32 v185, 1.0, v185
	v_add_f32_e32 v186, 1.0, v186
	v_add_f32_e32 v187, 1.0, v187
	v_add_f32_e32 v188, 1.0, v188
	v_add_f32_e32 v189, 1.0, v189
	v_add_f32_e32 v190, 1.0, v190
	v_rcp_f32_e32 v183, v183
	v_rcp_f32_e32 v184, v184
	v_rcp_f32_e32 v185, v185
	v_rcp_f32_e32 v186, v186
	v_rcp_f32_e32 v187, v187
	v_rcp_f32_e32 v188, v188
	v_rcp_f32_e32 v189, v189
	v_rcp_f32_e32 v190, v190
	v_fma_f32 v21, v183, v31, 0
	v_fmac_f32_e32 v21, v184, v32
	v_fmac_f32_e32 v21, v185, v160
	v_fmac_f32_e32 v21, v186, v161
	v_fmac_f32_e32 v21, v187, v162
	v_fmac_f32_e32 v21, v188, v163
	v_fmac_f32_e32 v21, v189, v199
	v_fmac_f32_e32 v21, v190, v200
	s_waitcnt vmcnt(8)
; __device__ __forceinline__ float bf2f(unsigned h) { return __uint_as_float(h << 16); }
; __device__ __forceinline__ float gelu_(float x) { return x * sigm_(1.5957691216f * (x + 0.044715f * x * x * x)); }
; __device__ __forceinline__ float wave_sum(float v) {
; #pragma unroll
;     for (int o = 1; o < 64; o <<= 1) v += __shfl_xor(v, o);
;     return v;
; __device__ __forceinline__ void gmlp_mfma(LAS unsigned char* lds, const unsigned char* R, bf16_t* O, const float* lng, const float* lnb, const float* wsp, const float* bsp, int unit, int tid) {
;     ...
;     for (int i = 0; i < 16; ++i) { const int t = w * 16 + i; const u32x4 x4 = *(const u32x4*)(VV + (r0 + t) * AW + lane * 8);
;         float x[8]; x[0] = gelu_(bf2f(x4.x & 0xffff)); x[1] = gelu_(bf2f(x4.x >> 16)); x[2] = gelu_(bf2f(x4.y & 0xffff)); x[3] = gelu_(bf2f(x4.y >> 16)); x[4] = gelu_(bf2f(x4.z & 0xffff)); x[5] = gelu_(bf2f(x4.z >> 16)); x[6] = gelu_(bf2f(x4.w & 0xffff)); x[7] = gelu_(bf2f(x4.w >> 16));
;         float s = 0.f;
; #pragma unroll
;         for (int j = 0; j < 8; ++j) s += x[j];
;         const float mean = wave_sum(s) * (1.f / 512.f); float q = 0.f;
	v_lshlrev_b32_e32 v31, 16, v124
	v_and_b32_e32 v32, 0xffff0000, v124
	v_lshlrev_b32_e32 v160, 16, v125
	v_and_b32_e32 v161, 0xffff0000, v125
	v_lshlrev_b32_e32 v162, 16, v126
	v_and_b32_e32 v163, 0xffff0000, v126
	v_lshlrev_b32_e32 v199, 16, v127
	v_and_b32_e32 v200, 0xffff0000, v127
	v_mul_f32_e32 v191, 0x3d372713, v31
	v_mul_f32_e32 v192, 0x3d372713, v32
	v_mul_f32_e32 v193, 0x3d372713, v160
	v_mul_f32_e32 v194, 0x3d372713, v161
	v_mul_f32_e32 v195, 0x3d372713, v162
	v_mul_f32_e32 v196, 0x3d372713, v163
	v_mul_f32_e32 v197, 0x3d372713, v199
	v_mul_f32_e32 v198, 0x3d372713, v200
	v_mul_f32_e32 v191, v191, v31
	v_mul_f32_e32 v192, v192, v32
	v_mul_f32_e32 v193, v193, v160
	v_mul_f32_e32 v194, v194, v161
	v_mul_f32_e32 v195, v195, v162
	v_mul_f32_e32 v196, v196, v163
	v_mul_f32_e32 v197, v197, v199
	v_mul_f32_e32 v198, v198, v200
	v_fma_f32 v191, v191, v31, v31
	v_fma_f32 v192, v192, v32, v32
	v_fma_f32 v193, v193, v160, v160
	v_fma_f32 v194, v194, v161, v161
	v_fma_f32 v195, v195, v162, v162
	v_fma_f32 v196, v196, v163, v163
	v_fma_f32 v197, v197, v199, v199
	v_fma_f32 v198, v198, v200, v200
	v_mul_f32_e32 v191, 0x3fcc422a, v191
	v_mul_f32_e32 v192, 0x3fcc422a, v192
	v_mul_f32_e32 v193, 0x3fcc422a, v193
	v_mul_f32_e32 v194, 0x3fcc422a, v194
	v_mul_f32_e32 v195, 0x3fcc422a, v195
	v_mul_f32_e32 v196, 0x3fcc422a, v196
	v_mul_f32_e32 v197, 0x3fcc422a, v197
	v_mul_f32_e32 v198, 0x3fcc422a, v198
	v_mul_f32_e32 v191, 0xbfb8aa3b, v191
	v_mul_f32_e32 v192, 0xbfb8aa3b, v192
	v_mul_f32_e32 v193, 0xbfb8aa3b, v193
	v_mul_f32_e32 v194, 0xbfb8aa3b, v194
	v_mul_f32_e32 v195, 0xbfb8aa3b, v195
	v_mul_f32_e32 v196, 0xbfb8aa3b, v196
	v_mul_f32_e32 v197, 0xbfb8aa3b, v197
	v_mul_f32_e32 v198, 0xbfb8aa3b, v198
	v_exp_f32_e32 v191, v191
	v_exp_f32_e32 v192, v192
	v_exp_f32_e32 v193, v193
	v_exp_f32_e32 v194, v194
	v_exp_f32_e32 v195, v195
	v_exp_f32_e32 v196, v196
	v_exp_f32_e32 v197, v197
	v_exp_f32_e32 v198, v198
	v_add_f32_e32 v191, 1.0, v191
	v_add_f32_e32 v192, 1.0, v192
	v_add_f32_e32 v193, 1.0, v193
	v_add_f32_e32 v194, 1.0, v194
	v_add_f32_e32 v195, 1.0, v195
	v_add_f32_e32 v196, 1.0, v196
	v_add_f32_e32 v197, 1.0, v197
	v_add_f32_e32 v198, 1.0, v198
	v_rcp_f32_e32 v191, v191
	v_rcp_f32_e32 v192, v192
	v_rcp_f32_e32 v193, v193
	v_rcp_f32_e32 v194, v194
	v_rcp_f32_e32 v195, v195
	v_rcp_f32_e32 v196, v196
	v_rcp_f32_e32 v197, v197
	v_rcp_f32_e32 v198, v198
	v_fma_f32 v22, v191, v31, 0
	v_fmac_f32_e32 v22, v192, v32
	v_fmac_f32_e32 v22, v193, v160
	v_fmac_f32_e32 v22, v194, v161
	v_fmac_f32_e32 v22, v195, v162
	v_fmac_f32_e32 v22, v196, v163
	v_fmac_f32_e32 v22, v197, v199
	v_fmac_f32_e32 v22, v198, v200
	ds_bpermute_b32 v31, v0, v15
	ds_bpermute_b32 v32, v0, v16
	ds_bpermute_b32 v160, v0, v17
	ds_bpermute_b32 v161, v0, v18
	ds_bpermute_b32 v162, v0, v19
	ds_bpermute_b32 v163, v0, v20
	ds_bpermute_b32 v199, v0, v21
	ds_bpermute_b32 v200, v0, v22
	s_waitcnt lgkmcnt(0)
	v_add_f32_e32 v15, v15, v31
	v_add_f32_e32 v16, v16, v32
	v_add_f32_e32 v17, v17, v160
	v_add_f32_e32 v18, v18, v161
	v_add_f32_e32 v19, v19, v162
	v_add_f32_e32 v20, v20, v163
	v_add_f32_e32 v21, v21, v199
	v_add_f32_e32 v22, v22, v200
	ds_bpermute_b32 v31, v10, v15
	ds_bpermute_b32 v32, v10, v16
	ds_bpermute_b32 v160, v10, v17
	ds_bpermute_b32 v161, v10, v18
	ds_bpermute_b32 v162, v10, v19
	ds_bpermute_b32 v163, v10, v20
	ds_bpermute_b32 v199, v10, v21
	ds_bpermute_b32 v200, v10, v22
	s_waitcnt lgkmcnt(0)
	v_add_f32_e32 v15, v15, v31
	v_add_f32_e32 v16, v16, v32
	v_add_f32_e32 v17, v17, v160
	v_add_f32_e32 v18, v18, v161
	v_add_f32_e32 v19, v19, v162
	v_add_f32_e32 v20, v20, v163
	v_add_f32_e32 v21, v21, v199
	v_add_f32_e32 v22, v22, v200
	ds_bpermute_b32 v31, v11, v15
	ds_bpermute_b32 v32, v11, v16
	ds_bpermute_b32 v160, v11, v17
	ds_bpermute_b32 v161, v11, v18
	ds_bpermute_b32 v162, v11, v19
	ds_bpermute_b32 v163, v11, v20
	ds_bpermute_b32 v199, v11, v21
	ds_bpermute_b32 v200, v11, v22
	s_waitcnt lgkmcnt(0)
	v_add_f32_e32 v15, v15, v31
	v_add_f32_e32 v16, v16, v32
	v_add_f32_e32 v17, v17, v160
	v_add_f32_e32 v18, v18, v161
	v_add_f32_e32 v19, v19, v162
	v_add_f32_e32 v20, v20, v163
	v_add_f32_e32 v21, v21, v199
	v_add_f32_e32 v22, v22, v200
	ds_bpermute_b32 v31, v12, v15
	ds_bpermute_b32 v32, v12, v16
	ds_bpermute_b32 v160, v12, v17
	ds_bpermute_b32 v161, v12, v18
	ds_bpermute_b32 v162, v12, v19
	ds_bpermute_b32 v163, v12, v20
	ds_bpermute_b32 v199, v12, v21
	ds_bpermute_b32 v200, v12, v22
	s_waitcnt lgkmcnt(0)
	v_add_f32_e32 v15, v15, v31
	v_add_f32_e32 v16, v16, v32
	v_add_f32_e32 v17, v17, v160
	v_add_f32_e32 v18, v18, v161
	v_add_f32_e32 v19, v19, v162
	v_add_f32_e32 v20, v20, v163
	v_add_f32_e32 v21, v21, v199
	v_add_f32_e32 v22, v22, v200
	ds_bpermute_b32 v31, v13, v15
	ds_bpermute_b32 v32, v13, v16
	ds_bpermute_b32 v160, v13, v17
	ds_bpermute_b32 v161, v13, v18
	ds_bpermute_b32 v162, v13, v19
	ds_bpermute_b32 v163, v13, v20
	ds_bpermute_b32 v199, v13, v21
	ds_bpermute_b32 v200, v13, v22
	s_waitcnt lgkmcnt(0)
	v_add_f32_e32 v15, v15, v31
	v_add_f32_e32 v16, v16, v32
	v_add_f32_e32 v17, v17, v160
	v_add_f32_e32 v18, v18, v161
	v_add_f32_e32 v19, v19, v162
	v_add_f32_e32 v20, v20, v163
	v_add_f32_e32 v21, v21, v199
	v_add_f32_e32 v22, v22, v200
	ds_bpermute_b32 v31, v14, v15
	ds_bpermute_b32 v32, v14, v16
	ds_bpermute_b32 v160, v14, v17
	ds_bpermute_b32 v161, v14, v18
	ds_bpermute_b32 v162, v14, v19
	ds_bpermute_b32 v163, v14, v20
	ds_bpermute_b32 v199, v14, v21
	ds_bpermute_b32 v200, v14, v22
	s_waitcnt lgkmcnt(0)
; __device__ __forceinline__ void gmlp_mfma(LAS unsigned char* lds, const unsigned char* R, bf16_t* O, const float* lng, const float* lnb, const float* wsp, const float* bsp, int unit, int tid) {
;     ...
;         const float mean = wave_sum(s) * (1.f / 512.f); float q = 0.f;
; #pragma unroll
;         for (int j = 0; j < 8; ++j) q += (x[j] - mean) * (x[j] - mean);
	v_add_f32_e32 v15, v15, v31
	v_add_f32_e32 v16, v16, v32
	v_add_f32_e32 v17, v17, v160
	v_add_f32_e32 v18, v18, v161
	v_add_f32_e32 v19, v19, v162
	v_add_f32_e32 v20, v20, v163
	v_add_f32_e32 v21, v21, v199
	v_add_f32_e32 v22, v22, v200
	v_mul_f32_e32 v15, 0x3b000000, v15
	v_mul_f32_e32 v16, 0x3b000000, v16
	v_mul_f32_e32 v17, 0x3b000000, v17
	v_mul_f32_e32 v18, 0x3b000000, v18
	v_mul_f32_e32 v19, 0x3b000000, v19
	v_mul_f32_e32 v20, 0x3b000000, v20
	v_mul_f32_e32 v21, 0x3b000000, v21
	v_mul_f32_e32 v22, 0x3b000000, v22
	v_lshlrev_b32_e32 v31, 16, v96
	v_and_b32_e32 v32, 0xffff0000, v96
	v_lshlrev_b32_e32 v160, 16, v97
	v_and_b32_e32 v161, 0xffff0000, v97
	v_lshlrev_b32_e32 v162, 16, v98
	v_and_b32_e32 v163, 0xffff0000, v98
	v_lshlrev_b32_e32 v199, 16, v99
	v_and_b32_e32 v200, 0xffff0000, v99
	v_fma_f32 v31, v210, v31, -v15
	v_fma_f32 v32, v211, v32, -v15
	v_fma_f32 v160, v212, v160, -v15
	v_fma_f32 v161, v213, v161, -v15
	v_fma_f32 v162, v214, v162, -v15
	v_fma_f32 v163, v215, v163, -v15
	v_fma_f32 v199, v216, v199, -v15
	v_fma_f32 v200, v217, v200, -v15
	v_mul_f32_e32 v23, v32, v32
	v_fmac_f32_e32 v23, v31, v31
	v_fmac_f32_e32 v23, v160, v160
	v_fmac_f32_e32 v23, v161, v161
	v_fmac_f32_e32 v23, v162, v162
	v_fmac_f32_e32 v23, v163, v163
	v_fmac_f32_e32 v23, v199, v199
	v_fmac_f32_e32 v23, v200, v200
	v_lshlrev_b32_e32 v31, 16, v100
	v_and_b32_e32 v32, 0xffff0000, v100
	v_lshlrev_b32_e32 v160, 16, v101
	v_and_b32_e32 v161, 0xffff0000, v101
	v_lshlrev_b32_e32 v162, 16, v102
	v_and_b32_e32 v163, 0xffff0000, v102
	v_lshlrev_b32_e32 v199, 16, v103
	v_and_b32_e32 v200, 0xffff0000, v103
	v_fma_f32 v31, v218, v31, -v16
	v_fma_f32 v32, v219, v32, -v16
	v_fma_f32 v160, v220, v160, -v16
	v_fma_f32 v161, v221, v161, -v16
	v_fma_f32 v162, v222, v162, -v16
	v_fma_f32 v163, v223, v163, -v16
	v_fma_f32 v199, v224, v199, -v16
	v_fma_f32 v200, v225, v200, -v16
	v_mul_f32_e32 v24, v32, v32
	v_fmac_f32_e32 v24, v31, v31
	v_fmac_f32_e32 v24, v160, v160
	v_fmac_f32_e32 v24, v161, v161
	v_fmac_f32_e32 v24, v162, v162
	v_fmac_f32_e32 v24, v163, v163
	v_fmac_f32_e32 v24, v199, v199
	v_fmac_f32_e32 v24, v200, v200
	v_lshlrev_b32_e32 v31, 16, v104
	v_and_b32_e32 v32, 0xffff0000, v104
	v_lshlrev_b32_e32 v160, 16, v105
	v_and_b32_e32 v161, 0xffff0000, v105
	v_lshlrev_b32_e32 v162, 16, v106
	v_and_b32_e32 v163, 0xffff0000, v106
	v_lshlrev_b32_e32 v199, 16, v107
	v_and_b32_e32 v200, 0xffff0000, v107
	v_fma_f32 v31, v226, v31, -v17
	v_fma_f32 v32, v227, v32, -v17
	v_fma_f32 v160, v228, v160, -v17
	v_fma_f32 v161, v229, v161, -v17
	v_fma_f32 v162, v230, v162, -v17
	v_fma_f32 v163, v231, v163, -v17
	v_fma_f32 v199, v232, v199, -v17
	v_fma_f32 v200, v233, v200, -v17
	v_mul_f32_e32 v25, v32, v32
	v_fmac_f32_e32 v25, v31, v31
	v_fmac_f32_e32 v25, v160, v160
	v_fmac_f32_e32 v25, v161, v161
	v_fmac_f32_e32 v25, v162, v162
	v_fmac_f32_e32 v25, v163, v163
	v_fmac_f32_e32 v25, v199, v199
	v_fmac_f32_e32 v25, v200, v200
	v_lshlrev_b32_e32 v31, 16, v108
	v_and_b32_e32 v32, 0xffff0000, v108
	v_lshlrev_b32_e32 v160, 16, v109
	v_and_b32_e32 v161, 0xffff0000, v109
	v_lshlrev_b32_e32 v162, 16, v110
	v_and_b32_e32 v163, 0xffff0000, v110
	v_lshlrev_b32_e32 v199, 16, v111
	v_and_b32_e32 v200, 0xffff0000, v111
	v_fma_f32 v31, v234, v31, -v18
	v_fma_f32 v32, v235, v32, -v18
	v_fma_f32 v160, v236, v160, -v18
	v_fma_f32 v161, v237, v161, -v18
	v_fma_f32 v162, v238, v162, -v18
	v_fma_f32 v163, v239, v163, -v18
	v_fma_f32 v199, v240, v199, -v18
	v_fma_f32 v200, v241, v200, -v18
	v_mul_f32_e32 v26, v32, v32
	v_fmac_f32_e32 v26, v31, v31
	v_fmac_f32_e32 v26, v160, v160
	v_fmac_f32_e32 v26, v161, v161
	v_fmac_f32_e32 v26, v162, v162
	v_fmac_f32_e32 v26, v163, v163
	v_fmac_f32_e32 v26, v199, v199
	v_fmac_f32_e32 v26, v200, v200
	v_lshlrev_b32_e32 v31, 16, v112
	v_and_b32_e32 v32, 0xffff0000, v112
	v_lshlrev_b32_e32 v160, 16, v113
	v_and_b32_e32 v161, 0xffff0000, v113
	v_lshlrev_b32_e32 v162, 16, v114
	v_and_b32_e32 v163, 0xffff0000, v114
	v_lshlrev_b32_e32 v199, 16, v115
	v_and_b32_e32 v200, 0xffff0000, v115
	v_fma_f32 v31, v242, v31, -v19
	v_fma_f32 v32, v243, v32, -v19
	v_fma_f32 v160, v244, v160, -v19
	v_fma_f32 v161, v245, v161, -v19
	v_fma_f32 v162, v246, v162, -v19
	v_fma_f32 v163, v247, v163, -v19
	v_fma_f32 v199, v248, v199, -v19
	v_fma_f32 v200, v249, v200, -v19
	v_mul_f32_e32 v27, v32, v32
	v_fmac_f32_e32 v27, v31, v31
	v_fmac_f32_e32 v27, v160, v160
	v_fmac_f32_e32 v27, v161, v161
	v_fmac_f32_e32 v27, v162, v162
	v_fmac_f32_e32 v27, v163, v163
	v_fmac_f32_e32 v27, v199, v199
	v_fmac_f32_e32 v27, v200, v200
	v_lshlrev_b32_e32 v31, 16, v116
	v_and_b32_e32 v32, 0xffff0000, v116
	v_lshlrev_b32_e32 v160, 16, v117
	v_and_b32_e32 v161, 0xffff0000, v117
	v_lshlrev_b32_e32 v162, 16, v118
	v_and_b32_e32 v163, 0xffff0000, v118
	v_lshlrev_b32_e32 v199, 16, v119
	v_and_b32_e32 v200, 0xffff0000, v119
	v_fma_f32 v31, v250, v31, -v20
	v_fma_f32 v32, v251, v32, -v20
	v_fma_f32 v160, v177, v160, -v20
	v_fma_f32 v161, v178, v161, -v20
	v_fma_f32 v162, v179, v162, -v20
	v_fma_f32 v163, v180, v163, -v20
	v_fma_f32 v199, v181, v199, -v20
	v_fma_f32 v200, v182, v200, -v20
	v_mul_f32_e32 v28, v32, v32
	v_fmac_f32_e32 v28, v31, v31
	v_fmac_f32_e32 v28, v160, v160
	v_fmac_f32_e32 v28, v161, v161
	v_fmac_f32_e32 v28, v162, v162
	v_fmac_f32_e32 v28, v163, v163
	v_fmac_f32_e32 v28, v199, v199
	v_fmac_f32_e32 v28, v200, v200
	v_lshlrev_b32_e32 v31, 16, v120
	v_and_b32_e32 v32, 0xffff0000, v120
	v_lshlrev_b32_e32 v160, 16, v121
	v_and_b32_e32 v161, 0xffff0000, v121
	v_lshlrev_b32_e32 v162, 16, v122
	v_and_b32_e32 v163, 0xffff0000, v122
	v_lshlrev_b32_e32 v199, 16, v123
	v_and_b32_e32 v200, 0xffff0000, v123
; __device__ __forceinline__ float wave_sum(float v) {
; #pragma unroll
;     for (int o = 1; o < 64; o <<= 1) v += __shfl_xor(v, o);
;     return v;
; __device__ __forceinline__ void gmlp_mfma(LAS unsigned char* lds, const unsigned char* R, bf16_t* O, const float* lng, const float* lnb, const float* wsp, const float* bsp, int unit, int tid) {
;     ...
;         for (int j = 0; j < 8; ++j) q += (x[j] - mean) * (x[j] - mean);
;         const float rstd = rsqrtf(wave_sum(q) * (1.f / 512.f) + EPS);
	v_fma_f32 v31, v183, v31, -v21
	v_fma_f32 v32, v184, v32, -v21
	v_fma_f32 v160, v185, v160, -v21
	v_fma_f32 v161, v186, v161, -v21
	v_fma_f32 v162, v187, v162, -v21
	v_fma_f32 v163, v188, v163, -v21
	v_fma_f32 v199, v189, v199, -v21
	v_fma_f32 v200, v190, v200, -v21
	v_mul_f32_e32 v29, v32, v32
	v_fmac_f32_e32 v29, v31, v31
	v_fmac_f32_e32 v29, v160, v160
	v_fmac_f32_e32 v29, v161, v161
	v_fmac_f32_e32 v29, v162, v162
	v_fmac_f32_e32 v29, v163, v163
	v_fmac_f32_e32 v29, v199, v199
	v_fmac_f32_e32 v29, v200, v200
	v_lshlrev_b32_e32 v31, 16, v124
	v_and_b32_e32 v32, 0xffff0000, v124
	v_lshlrev_b32_e32 v160, 16, v125
	v_and_b32_e32 v161, 0xffff0000, v125
	v_lshlrev_b32_e32 v162, 16, v126
	v_and_b32_e32 v163, 0xffff0000, v126
	v_lshlrev_b32_e32 v199, 16, v127
	v_and_b32_e32 v200, 0xffff0000, v127
	v_fma_f32 v31, v191, v31, -v22
	v_fma_f32 v32, v192, v32, -v22
	v_fma_f32 v160, v193, v160, -v22
	v_fma_f32 v161, v194, v161, -v22
	v_fma_f32 v162, v195, v162, -v22
	v_fma_f32 v163, v196, v163, -v22
	v_fma_f32 v199, v197, v199, -v22
	v_fma_f32 v200, v198, v200, -v22
	v_mul_f32_e32 v30, v32, v32
	v_fmac_f32_e32 v30, v31, v31
	v_fmac_f32_e32 v30, v160, v160
	v_fmac_f32_e32 v30, v161, v161
	v_fmac_f32_e32 v30, v162, v162
	v_fmac_f32_e32 v30, v163, v163
	v_fmac_f32_e32 v30, v199, v199
	v_fmac_f32_e32 v30, v200, v200
	ds_bpermute_b32 v31, v0, v23
	ds_bpermute_b32 v32, v0, v24
	ds_bpermute_b32 v160, v0, v25
	ds_bpermute_b32 v161, v0, v26
	ds_bpermute_b32 v162, v0, v27
	ds_bpermute_b32 v163, v0, v28
	ds_bpermute_b32 v199, v0, v29
	ds_bpermute_b32 v200, v0, v30
	s_waitcnt lgkmcnt(0)
	v_add_f32_e32 v23, v23, v31
	v_add_f32_e32 v24, v24, v32
	v_add_f32_e32 v25, v25, v160
	v_add_f32_e32 v26, v26, v161
	v_add_f32_e32 v27, v27, v162
	v_add_f32_e32 v28, v28, v163
	v_add_f32_e32 v29, v29, v199
	v_add_f32_e32 v30, v30, v200
	ds_bpermute_b32 v31, v10, v23
	ds_bpermute_b32 v32, v10, v24
	ds_bpermute_b32 v160, v10, v25
	ds_bpermute_b32 v161, v10, v26
	ds_bpermute_b32 v162, v10, v27
	ds_bpermute_b32 v163, v10, v28
	ds_bpermute_b32 v199, v10, v29
	ds_bpermute_b32 v200, v10, v30
	s_waitcnt lgkmcnt(0)
	v_add_f32_e32 v23, v23, v31
	v_add_f32_e32 v24, v24, v32
	v_add_f32_e32 v25, v25, v160
	v_add_f32_e32 v26, v26, v161
	v_add_f32_e32 v27, v27, v162
	v_add_f32_e32 v28, v28, v163
	v_add_f32_e32 v29, v29, v199
	v_add_f32_e32 v30, v30, v200
	ds_bpermute_b32 v31, v11, v23
	ds_bpermute_b32 v32, v11, v24
	ds_bpermute_b32 v160, v11, v25
	ds_bpermute_b32 v161, v11, v26
	ds_bpermute_b32 v162, v11, v27
	ds_bpermute_b32 v163, v11, v28
	ds_bpermute_b32 v199, v11, v29
	ds_bpermute_b32 v200, v11, v30
	s_waitcnt lgkmcnt(0)
	v_add_f32_e32 v23, v23, v31
	v_add_f32_e32 v24, v24, v32
	v_add_f32_e32 v25, v25, v160
	v_add_f32_e32 v26, v26, v161
	v_add_f32_e32 v27, v27, v162
	v_add_f32_e32 v28, v28, v163
	v_add_f32_e32 v29, v29, v199
	v_add_f32_e32 v30, v30, v200
	ds_bpermute_b32 v31, v12, v23
	ds_bpermute_b32 v32, v12, v24
	ds_bpermute_b32 v160, v12, v25
	ds_bpermute_b32 v161, v12, v26
	ds_bpermute_b32 v162, v12, v27
	ds_bpermute_b32 v163, v12, v28
	ds_bpermute_b32 v199, v12, v29
	ds_bpermute_b32 v200, v12, v30
	s_waitcnt lgkmcnt(0)
	v_add_f32_e32 v23, v23, v31
	v_add_f32_e32 v24, v24, v32
	v_add_f32_e32 v25, v25, v160
	v_add_f32_e32 v26, v26, v161
	v_add_f32_e32 v27, v27, v162
	v_add_f32_e32 v28, v28, v163
	v_add_f32_e32 v29, v29, v199
	v_add_f32_e32 v30, v30, v200
	ds_bpermute_b32 v31, v13, v23
	ds_bpermute_b32 v32, v13, v24
	ds_bpermute_b32 v160, v13, v25
	ds_bpermute_b32 v161, v13, v26
	ds_bpermute_b32 v162, v13, v27
	ds_bpermute_b32 v163, v13, v28
	ds_bpermute_b32 v199, v13, v29
	ds_bpermute_b32 v200, v13, v30
	s_waitcnt lgkmcnt(0)
	v_add_f32_e32 v23, v23, v31
	v_add_f32_e32 v24, v24, v32
	v_add_f32_e32 v25, v25, v160
	v_add_f32_e32 v26, v26, v161
	v_add_f32_e32 v27, v27, v162
	v_add_f32_e32 v28, v28, v163
	v_add_f32_e32 v29, v29, v199
	v_add_f32_e32 v30, v30, v200
	ds_bpermute_b32 v31, v14, v23
	ds_bpermute_b32 v32, v14, v24
	ds_bpermute_b32 v160, v14, v25
	ds_bpermute_b32 v161, v14, v26
	ds_bpermute_b32 v162, v14, v27
	ds_bpermute_b32 v163, v14, v28
	ds_bpermute_b32 v199, v14, v29
	ds_bpermute_b32 v200, v14, v30
	s_waitcnt lgkmcnt(0)
	v_add_f32_e32 v23, v23, v31
	v_add_f32_e32 v24, v24, v32
	v_add_f32_e32 v25, v25, v160
	v_add_f32_e32 v26, v26, v161
	v_add_f32_e32 v27, v27, v162
	v_add_f32_e32 v28, v28, v163
	v_add_f32_e32 v29, v29, v199
	v_add_f32_e32 v30, v30, v200
	v_fmamk_f32 v23, v23, 0x3b000000, v204
	v_fmamk_f32 v24, v24, 0x3b000000, v204
	v_fmamk_f32 v25, v25, 0x3b000000, v204
	v_fmamk_f32 v26, v26, 0x3b000000, v204
	v_fmamk_f32 v27, v27, 0x3b000000, v204
	v_fmamk_f32 v28, v28, 0x3b000000, v204
	v_fmamk_f32 v29, v29, 0x3b000000, v204
	v_fmamk_f32 v30, v30, 0x3b000000, v204
	v_cmp_gt_f32_e32 vcc, s24, v23
	v_mul_f32_e32 v31, 0x4b800000, v23
	s_nop 0
	v_cndmask_b32_e32 v23, v23, v31, vcc
	v_rsq_f32_e32 v23, v23
	s_nop 0
	v_mul_f32_e32 v31, 0x45800000, v23
	v_cndmask_b32_e32 v23, v23, v31, vcc
	v_cmp_gt_f32_e32 vcc, s24, v24
	v_mul_f32_e32 v31, 0x4b800000, v24
	s_nop 0
	v_cndmask_b32_e32 v24, v24, v31, vcc
	v_rsq_f32_e32 v24, v24
	s_nop 0
	v_mul_f32_e32 v31, 0x45800000, v24
	v_cndmask_b32_e32 v24, v24, v31, vcc
	v_cmp_gt_f32_e32 vcc, s24, v25
	v_mul_f32_e32 v31, 0x4b800000, v25
	s_nop 0
	v_cndmask_b32_e32 v25, v25, v31, vcc
	v_rsq_f32_e32 v25, v25
	s_nop 0
	v_mul_f32_e32 v31, 0x45800000, v25
	v_cndmask_b32_e32 v25, v25, v31, vcc
	v_cmp_gt_f32_e32 vcc, s24, v26
	v_mul_f32_e32 v31, 0x4b800000, v26
	s_nop 0
	v_cndmask_b32_e32 v26, v26, v31, vcc
	v_rsq_f32_e32 v26, v26
	s_nop 0
	v_mul_f32_e32 v31, 0x45800000, v26
	v_cndmask_b32_e32 v26, v26, v31, vcc
	v_cmp_gt_f32_e32 vcc, s24, v27
; __device__ __forceinline__ float bf2f(unsigned h) { return __uint_as_float(h << 16); }
; __device__ __forceinline__ float gelu_(float x) { return x * sigm_(1.5957691216f * (x + 0.044715f * x * x * x)); }
; __device__ __forceinline__ void gmlp_mfma(LAS unsigned char* lds, const unsigned char* R, bf16_t* O, const float* lng, const float* lnb, const float* wsp, const float* bsp, int unit, int tid) {
;     ...
;     for (int i = 0; i < 16; ++i) { const int t = w * 16 + i; const u32x4 x4 = *(const u32x4*)(VV + (r0 + t) * AW + lane * 8);
;         float x[8]; x[0] = gelu_(bf2f(x4.x & 0xffff)); x[1] = gelu_(bf2f(x4.x >> 16)); x[2] = gelu_(bf2f(x4.y & 0xffff)); x[3] = gelu_(bf2f(x4.y >> 16)); x[4] = gelu_(bf2f(x4.z & 0xffff)); x[5] = gelu_(bf2f(x4.z >> 16)); x[6] = gelu_(bf2f(x4.w & 0xffff)); x[7] = gelu_(bf2f(x4.w >> 16));
;         float s = 0.f;
; #pragma unroll
;         for (int j = 0; j < 8; ++j) s += x[j];
;     ...
;         const float rstd = rsqrtf(wave_sum(q) * (1.f / 512.f) + EPS);
;         if (lane == 0) { mu[t] = mean; rs[t] = rstd; } }
	v_mul_f32_e32 v31, 0x4b800000, v27
	s_nop 0
	v_cndmask_b32_e32 v27, v27, v31, vcc
	v_rsq_f32_e32 v27, v27
	s_nop 0
	v_mul_f32_e32 v31, 0x45800000, v27
	v_cndmask_b32_e32 v27, v27, v31, vcc
	v_cmp_gt_f32_e32 vcc, s24, v28
	v_mul_f32_e32 v31, 0x4b800000, v28
	s_nop 0
	v_cndmask_b32_e32 v28, v28, v31, vcc
	v_rsq_f32_e32 v28, v28
	s_nop 0
	v_mul_f32_e32 v31, 0x45800000, v28
	v_cndmask_b32_e32 v28, v28, v31, vcc
	v_cmp_gt_f32_e32 vcc, s24, v29
	v_mul_f32_e32 v31, 0x4b800000, v29
	s_nop 0
	v_cndmask_b32_e32 v29, v29, v31, vcc
	v_rsq_f32_e32 v29, v29
	s_nop 0
	v_mul_f32_e32 v31, 0x45800000, v29
	v_cndmask_b32_e32 v29, v29, v31, vcc
	v_cmp_gt_f32_e32 vcc, s24, v30
	v_mul_f32_e32 v31, 0x4b800000, v30
	s_nop 0
	v_cndmask_b32_e32 v30, v30, v31, vcc
	v_rsq_f32_e32 v30, v30
	s_nop 0
	v_mul_f32_e32 v31, 0x45800000, v30
	v_cndmask_b32_e32 v30, v30, v31, vcc
	v_mov_b32_e32 v32, s19
	v_add_u32_e32 v32, 0x11000, v32
	s_and_saveexec_b64 s[14:15], s[42:43]
	ds_write_b32 v32, v15 offset:0
	ds_write_b32 v32, v23 offset:512
	ds_write_b32 v32, v16 offset:4
	ds_write_b32 v32, v24 offset:516
	ds_write_b32 v32, v17 offset:8
	ds_write_b32 v32, v25 offset:520
	ds_write_b32 v32, v18 offset:12
	ds_write_b32 v32, v26 offset:524
	ds_write_b32 v32, v19 offset:16
	ds_write_b32 v32, v27 offset:528
	ds_write_b32 v32, v20 offset:20
	ds_write_b32 v32, v28 offset:532
	ds_write_b32 v32, v21 offset:24
	ds_write_b32 v32, v29 offset:536
	ds_write_b32 v32, v22 offset:28
	ds_write_b32 v32, v30 offset:540
	s_or_b64 exec, exec, s[14:15]
	s_waitcnt vmcnt(7)
	v_lshlrev_b32_e32 v31, 16, v128
	v_and_b32_e32 v32, 0xffff0000, v128
	v_lshlrev_b32_e32 v160, 16, v129
	v_and_b32_e32 v161, 0xffff0000, v129
	v_lshlrev_b32_e32 v162, 16, v130
	v_and_b32_e32 v163, 0xffff0000, v130
	v_lshlrev_b32_e32 v199, 16, v131
	v_and_b32_e32 v200, 0xffff0000, v131
	v_mul_f32_e32 v210, 0x3d372713, v31
	v_mul_f32_e32 v211, 0x3d372713, v32
	v_mul_f32_e32 v212, 0x3d372713, v160
	v_mul_f32_e32 v213, 0x3d372713, v161
	v_mul_f32_e32 v214, 0x3d372713, v162
	v_mul_f32_e32 v215, 0x3d372713, v163
	v_mul_f32_e32 v216, 0x3d372713, v199
	v_mul_f32_e32 v217, 0x3d372713, v200
	v_mul_f32_e32 v210, v210, v31
	v_mul_f32_e32 v211, v211, v32
	v_mul_f32_e32 v212, v212, v160
	v_mul_f32_e32 v213, v213, v161
	v_mul_f32_e32 v214, v214, v162
	v_mul_f32_e32 v215, v215, v163
	v_mul_f32_e32 v216, v216, v199
	v_mul_f32_e32 v217, v217, v200
	v_fma_f32 v210, v210, v31, v31
	v_fma_f32 v211, v211, v32, v32
	v_fma_f32 v212, v212, v160, v160
	v_fma_f32 v213, v213, v161, v161
	v_fma_f32 v214, v214, v162, v162
	v_fma_f32 v215, v215, v163, v163
	v_fma_f32 v216, v216, v199, v199
	v_fma_f32 v217, v217, v200, v200
	v_mul_f32_e32 v210, 0x3fcc422a, v210
	v_mul_f32_e32 v211, 0x3fcc422a, v211
	v_mul_f32_e32 v212, 0x3fcc422a, v212
	v_mul_f32_e32 v213, 0x3fcc422a, v213
	v_mul_f32_e32 v214, 0x3fcc422a, v214
	v_mul_f32_e32 v215, 0x3fcc422a, v215
	v_mul_f32_e32 v216, 0x3fcc422a, v216
	v_mul_f32_e32 v217, 0x3fcc422a, v217
	v_mul_f32_e32 v210, 0xbfb8aa3b, v210
	v_mul_f32_e32 v211, 0xbfb8aa3b, v211
	v_mul_f32_e32 v212, 0xbfb8aa3b, v212
	v_mul_f32_e32 v213, 0xbfb8aa3b, v213
	v_mul_f32_e32 v214, 0xbfb8aa3b, v214
	v_mul_f32_e32 v215, 0xbfb8aa3b, v215
	v_mul_f32_e32 v216, 0xbfb8aa3b, v216
	v_mul_f32_e32 v217, 0xbfb8aa3b, v217
	v_exp_f32_e32 v210, v210
	v_exp_f32_e32 v211, v211
	v_exp_f32_e32 v212, v212
	v_exp_f32_e32 v213, v213
	v_exp_f32_e32 v214, v214
	v_exp_f32_e32 v215, v215
	v_exp_f32_e32 v216, v216
	v_exp_f32_e32 v217, v217
	v_add_f32_e32 v210, 1.0, v210
	v_add_f32_e32 v211, 1.0, v211
	v_add_f32_e32 v212, 1.0, v212
	v_add_f32_e32 v213, 1.0, v213
	v_add_f32_e32 v214, 1.0, v214
	v_add_f32_e32 v215, 1.0, v215
	v_add_f32_e32 v216, 1.0, v216
	v_add_f32_e32 v217, 1.0, v217
	v_rcp_f32_e32 v210, v210
	v_rcp_f32_e32 v211, v211
	v_rcp_f32_e32 v212, v212
	v_rcp_f32_e32 v213, v213
	v_rcp_f32_e32 v214, v214
	v_rcp_f32_e32 v215, v215
	v_rcp_f32_e32 v216, v216
	v_rcp_f32_e32 v217, v217
	v_fma_f32 v15, v210, v31, 0
	v_fmac_f32_e32 v15, v211, v32
	v_fmac_f32_e32 v15, v212, v160
	v_fmac_f32_e32 v15, v213, v161
	v_fmac_f32_e32 v15, v214, v162
	v_fmac_f32_e32 v15, v215, v163
	v_fmac_f32_e32 v15, v216, v199
	v_fmac_f32_e32 v15, v217, v200
	s_waitcnt vmcnt(6)
	v_lshlrev_b32_e32 v31, 16, v132
	v_and_b32_e32 v32, 0xffff0000, v132
	v_lshlrev_b32_e32 v160, 16, v133
	v_and_b32_e32 v161, 0xffff0000, v133
	v_lshlrev_b32_e32 v162, 16, v134
	v_and_b32_e32 v163, 0xffff0000, v134
	v_lshlrev_b32_e32 v199, 16, v135
	v_and_b32_e32 v200, 0xffff0000, v135
	v_mul_f32_e32 v218, 0x3d372713, v31
	v_mul_f32_e32 v219, 0x3d372713, v32
	v_mul_f32_e32 v220, 0x3d372713, v160
	v_mul_f32_e32 v221, 0x3d372713, v161
	v_mul_f32_e32 v222, 0x3d372713, v162
	v_mul_f32_e32 v223, 0x3d372713, v163
	v_mul_f32_e32 v224, 0x3d372713, v199
	v_mul_f32_e32 v225, 0x3d372713, v200
	v_mul_f32_e32 v218, v218, v31
	v_mul_f32_e32 v219, v219, v32
	v_mul_f32_e32 v220, v220, v160
	v_mul_f32_e32 v221, v221, v161
	v_mul_f32_e32 v222, v222, v162
	v_mul_f32_e32 v223, v223, v163
	v_mul_f32_e32 v224, v224, v199
	v_mul_f32_e32 v225, v225, v200
	v_fma_f32 v218, v218, v31, v31
	v_fma_f32 v219, v219, v32, v32
	v_fma_f32 v220, v220, v160, v160
	v_fma_f32 v221, v221, v161, v161
	v_fma_f32 v222, v222, v162, v162
	v_fma_f32 v223, v223, v163, v163
	v_fma_f32 v224, v224, v199, v199
	v_fma_f32 v225, v225, v200, v200
	v_mul_f32_e32 v218, 0x3fcc422a, v218
	v_mul_f32_e32 v219, 0x3fcc422a, v219
	v_mul_f32_e32 v220, 0x3fcc422a, v220
	v_mul_f32_e32 v221, 0x3fcc422a, v221
	v_mul_f32_e32 v222, 0x3fcc422a, v222
	v_mul_f32_e32 v223, 0x3fcc422a, v223
	v_mul_f32_e32 v224, 0x3fcc422a, v224
	v_mul_f32_e32 v225, 0x3fcc422a, v225
	v_mul_f32_e32 v218, 0xbfb8aa3b, v218
	v_mul_f32_e32 v219, 0xbfb8aa3b, v219
	v_mul_f32_e32 v220, 0xbfb8aa3b, v220
	v_mul_f32_e32 v221, 0xbfb8aa3b, v221
	v_mul_f32_e32 v222, 0xbfb8aa3b, v222
	v_mul_f32_e32 v223, 0xbfb8aa3b, v223
	v_mul_f32_e32 v224, 0xbfb8aa3b, v224
	v_mul_f32_e32 v225, 0xbfb8aa3b, v225
	v_exp_f32_e32 v218, v218
	v_exp_f32_e32 v219, v219
	v_exp_f32_e32 v220, v220
	v_exp_f32_e32 v221, v221
	v_exp_f32_e32 v222, v222
	v_exp_f32_e32 v223, v223
	v_exp_f32_e32 v224, v224
	v_exp_f32_e32 v225, v225
	v_add_f32_e32 v218, 1.0, v218
	v_add_f32_e32 v219, 1.0, v219
	v_add_f32_e32 v220, 1.0, v220
	v_add_f32_e32 v221, 1.0, v221
	v_add_f32_e32 v222, 1.0, v222
	v_add_f32_e32 v223, 1.0, v223
	v_add_f32_e32 v224, 1.0, v224
	v_add_f32_e32 v225, 1.0, v225
	v_rcp_f32_e32 v218, v218
	v_rcp_f32_e32 v219, v219
	v_rcp_f32_e32 v220, v220
	v_rcp_f32_e32 v221, v221
	v_rcp_f32_e32 v222, v222
	v_rcp_f32_e32 v223, v223
	v_rcp_f32_e32 v224, v224
	v_rcp_f32_e32 v225, v225
	v_fma_f32 v16, v218, v31, 0
	v_fmac_f32_e32 v16, v219, v32
	v_fmac_f32_e32 v16, v220, v160
	v_fmac_f32_e32 v16, v221, v161
	v_fmac_f32_e32 v16, v222, v162
	v_fmac_f32_e32 v16, v223, v163
	v_fmac_f32_e32 v16, v224, v199
	v_fmac_f32_e32 v16, v225, v200
	s_waitcnt vmcnt(5)
; __device__ __forceinline__ float bf2f(unsigned h) { return __uint_as_float(h << 16); }
; __device__ __forceinline__ float gelu_(float x) { return x * sigm_(1.5957691216f * (x + 0.044715f * x * x * x)); }
; __device__ __forceinline__ void gmlp_mfma(LAS unsigned char* lds, const unsigned char* R, bf16_t* O, const float* lng, const float* lnb, const float* wsp, const float* bsp, int unit, int tid) {
;     ...
;     for (int i = 0; i < 16; ++i) { const int t = w * 16 + i; const u32x4 x4 = *(const u32x4*)(VV + (r0 + t) * AW + lane * 8);
;         float x[8]; x[0] = gelu_(bf2f(x4.x & 0xffff)); x[1] = gelu_(bf2f(x4.x >> 16)); x[2] = gelu_(bf2f(x4.y & 0xffff)); x[3] = gelu_(bf2f(x4.y >> 16)); x[4] = gelu_(bf2f(x4.z & 0xffff)); x[5] = gelu_(bf2f(x4.z >> 16)); x[6] = gelu_(bf2f(x4.w & 0xffff)); x[7] = gelu_(bf2f(x4.w >> 16));
;         float s = 0.f;
; #pragma unroll
;         for (int j = 0; j < 8; ++j) s += x[j];
	v_lshlrev_b32_e32 v31, 16, v136
	v_and_b32_e32 v32, 0xffff0000, v136
	v_lshlrev_b32_e32 v160, 16, v137
	v_and_b32_e32 v161, 0xffff0000, v137
	v_lshlrev_b32_e32 v162, 16, v138
	v_and_b32_e32 v163, 0xffff0000, v138
	v_lshlrev_b32_e32 v199, 16, v139
	v_and_b32_e32 v200, 0xffff0000, v139
	v_mul_f32_e32 v226, 0x3d372713, v31
	v_mul_f32_e32 v227, 0x3d372713, v32
	v_mul_f32_e32 v228, 0x3d372713, v160
	v_mul_f32_e32 v229, 0x3d372713, v161
	v_mul_f32_e32 v230, 0x3d372713, v162
	v_mul_f32_e32 v231, 0x3d372713, v163
	v_mul_f32_e32 v232, 0x3d372713, v199
	v_mul_f32_e32 v233, 0x3d372713, v200
	v_mul_f32_e32 v226, v226, v31
	v_mul_f32_e32 v227, v227, v32
	v_mul_f32_e32 v228, v228, v160
	v_mul_f32_e32 v229, v229, v161
	v_mul_f32_e32 v230, v230, v162
	v_mul_f32_e32 v231, v231, v163
	v_mul_f32_e32 v232, v232, v199
	v_mul_f32_e32 v233, v233, v200
	v_fma_f32 v226, v226, v31, v31
	v_fma_f32 v227, v227, v32, v32
	v_fma_f32 v228, v228, v160, v160
	v_fma_f32 v229, v229, v161, v161
	v_fma_f32 v230, v230, v162, v162
	v_fma_f32 v231, v231, v163, v163
	v_fma_f32 v232, v232, v199, v199
	v_fma_f32 v233, v233, v200, v200
	v_mul_f32_e32 v226, 0x3fcc422a, v226
	v_mul_f32_e32 v227, 0x3fcc422a, v227
	v_mul_f32_e32 v228, 0x3fcc422a, v228
	v_mul_f32_e32 v229, 0x3fcc422a, v229
	v_mul_f32_e32 v230, 0x3fcc422a, v230
	v_mul_f32_e32 v231, 0x3fcc422a, v231
	v_mul_f32_e32 v232, 0x3fcc422a, v232
	v_mul_f32_e32 v233, 0x3fcc422a, v233
	v_mul_f32_e32 v226, 0xbfb8aa3b, v226
	v_mul_f32_e32 v227, 0xbfb8aa3b, v227
	v_mul_f32_e32 v228, 0xbfb8aa3b, v228
	v_mul_f32_e32 v229, 0xbfb8aa3b, v229
	v_mul_f32_e32 v230, 0xbfb8aa3b, v230
	v_mul_f32_e32 v231, 0xbfb8aa3b, v231
	v_mul_f32_e32 v232, 0xbfb8aa3b, v232
	v_mul_f32_e32 v233, 0xbfb8aa3b, v233
	v_exp_f32_e32 v226, v226
	v_exp_f32_e32 v227, v227
	v_exp_f32_e32 v228, v228
	v_exp_f32_e32 v229, v229
	v_exp_f32_e32 v230, v230
	v_exp_f32_e32 v231, v231
	v_exp_f32_e32 v232, v232
	v_exp_f32_e32 v233, v233
	v_add_f32_e32 v226, 1.0, v226
	v_add_f32_e32 v227, 1.0, v227
	v_add_f32_e32 v228, 1.0, v228
	v_add_f32_e32 v229, 1.0, v229
	v_add_f32_e32 v230, 1.0, v230
	v_add_f32_e32 v231, 1.0, v231
	v_add_f32_e32 v232, 1.0, v232
	v_add_f32_e32 v233, 1.0, v233
	v_rcp_f32_e32 v226, v226
	v_rcp_f32_e32 v227, v227
	v_rcp_f32_e32 v228, v228
	v_rcp_f32_e32 v229, v229
	v_rcp_f32_e32 v230, v230
	v_rcp_f32_e32 v231, v231
	v_rcp_f32_e32 v232, v232
	v_rcp_f32_e32 v233, v233
	v_fma_f32 v17, v226, v31, 0
	v_fmac_f32_e32 v17, v227, v32
	v_fmac_f32_e32 v17, v228, v160
	v_fmac_f32_e32 v17, v229, v161
	v_fmac_f32_e32 v17, v230, v162
	v_fmac_f32_e32 v17, v231, v163
	v_fmac_f32_e32 v17, v232, v199
	v_fmac_f32_e32 v17, v233, v200
	s_waitcnt vmcnt(4)
	v_lshlrev_b32_e32 v31, 16, v140
	v_and_b32_e32 v32, 0xffff0000, v140
	v_lshlrev_b32_e32 v160, 16, v141
	v_and_b32_e32 v161, 0xffff0000, v141
	v_lshlrev_b32_e32 v162, 16, v142
	v_and_b32_e32 v163, 0xffff0000, v142
	v_lshlrev_b32_e32 v199, 16, v143
	v_and_b32_e32 v200, 0xffff0000, v143
	v_mul_f32_e32 v234, 0x3d372713, v31
	v_mul_f32_e32 v235, 0x3d372713, v32
	v_mul_f32_e32 v236, 0x3d372713, v160
	v_mul_f32_e32 v237, 0x3d372713, v161
	v_mul_f32_e32 v238, 0x3d372713, v162
	v_mul_f32_e32 v239, 0x3d372713, v163
	v_mul_f32_e32 v240, 0x3d372713, v199
	v_mul_f32_e32 v241, 0x3d372713, v200
	v_mul_f32_e32 v234, v234, v31
	v_mul_f32_e32 v235, v235, v32
	v_mul_f32_e32 v236, v236, v160
	v_mul_f32_e32 v237, v237, v161
	v_mul_f32_e32 v238, v238, v162
	v_mul_f32_e32 v239, v239, v163
	v_mul_f32_e32 v240, v240, v199
	v_mul_f32_e32 v241, v241, v200
	v_fma_f32 v234, v234, v31, v31
	v_fma_f32 v235, v235, v32, v32
	v_fma_f32 v236, v236, v160, v160
	v_fma_f32 v237, v237, v161, v161
	v_fma_f32 v238, v238, v162, v162
	v_fma_f32 v239, v239, v163, v163
	v_fma_f32 v240, v240, v199, v199
	v_fma_f32 v241, v241, v200, v200
	v_mul_f32_e32 v234, 0x3fcc422a, v234
	v_mul_f32_e32 v235, 0x3fcc422a, v235
	v_mul_f32_e32 v236, 0x3fcc422a, v236
	v_mul_f32_e32 v237, 0x3fcc422a, v237
	v_mul_f32_e32 v238, 0x3fcc422a, v238
	v_mul_f32_e32 v239, 0x3fcc422a, v239
	v_mul_f32_e32 v240, 0x3fcc422a, v240
	v_mul_f32_e32 v241, 0x3fcc422a, v241
	v_mul_f32_e32 v234, 0xbfb8aa3b, v234
	v_mul_f32_e32 v235, 0xbfb8aa3b, v235
	v_mul_f32_e32 v236, 0xbfb8aa3b, v236
	v_mul_f32_e32 v237, 0xbfb8aa3b, v237
	v_mul_f32_e32 v238, 0xbfb8aa3b, v238
	v_mul_f32_e32 v239, 0xbfb8aa3b, v239
	v_mul_f32_e32 v240, 0xbfb8aa3b, v240
	v_mul_f32_e32 v241, 0xbfb8aa3b, v241
	v_exp_f32_e32 v234, v234
	v_exp_f32_e32 v235, v235
	v_exp_f32_e32 v236, v236
	v_exp_f32_e32 v237, v237
	v_exp_f32_e32 v238, v238
	v_exp_f32_e32 v239, v239
	v_exp_f32_e32 v240, v240
	v_exp_f32_e32 v241, v241
	v_add_f32_e32 v234, 1.0, v234
	v_add_f32_e32 v235, 1.0, v235
	v_add_f32_e32 v236, 1.0, v236
	v_add_f32_e32 v237, 1.0, v237
	v_add_f32_e32 v238, 1.0, v238
	v_add_f32_e32 v239, 1.0, v239
	v_add_f32_e32 v240, 1.0, v240
	v_add_f32_e32 v241, 1.0, v241
	v_rcp_f32_e32 v234, v234
	v_rcp_f32_e32 v235, v235
	v_rcp_f32_e32 v236, v236
	v_rcp_f32_e32 v237, v237
	v_rcp_f32_e32 v238, v238
	v_rcp_f32_e32 v239, v239
	v_rcp_f32_e32 v240, v240
	v_rcp_f32_e32 v241, v241
	v_fma_f32 v18, v234, v31, 0
	v_fmac_f32_e32 v18, v235, v32
	v_fmac_f32_e32 v18, v236, v160
	v_fmac_f32_e32 v18, v237, v161
	v_fmac_f32_e32 v18, v238, v162
	v_fmac_f32_e32 v18, v239, v163
	v_fmac_f32_e32 v18, v240, v199
	v_fmac_f32_e32 v18, v241, v200
	s_waitcnt vmcnt(3)
; __device__ __forceinline__ float bf2f(unsigned h) { return __uint_as_float(h << 16); }
; __device__ __forceinline__ float gelu_(float x) { return x * sigm_(1.5957691216f * (x + 0.044715f * x * x * x)); }
; __device__ __forceinline__ void gmlp_mfma(LAS unsigned char* lds, const unsigned char* R, bf16_t* O, const float* lng, const float* lnb, const float* wsp, const float* bsp, int unit, int tid) {
;     ...
;     for (int i = 0; i < 16; ++i) { const int t = w * 16 + i; const u32x4 x4 = *(const u32x4*)(VV + (r0 + t) * AW + lane * 8);
;         float x[8]; x[0] = gelu_(bf2f(x4.x & 0xffff)); x[1] = gelu_(bf2f(x4.x >> 16)); x[2] = gelu_(bf2f(x4.y & 0xffff)); x[3] = gelu_(bf2f(x4.y >> 16)); x[4] = gelu_(bf2f(x4.z & 0xffff)); x[5] = gelu_(bf2f(x4.z >> 16)); x[6] = gelu_(bf2f(x4.w & 0xffff)); x[7] = gelu_(bf2f(x4.w >> 16));
;         float s = 0.f;
; #pragma unroll
;         for (int j = 0; j < 8; ++j) s += x[j];
	v_lshlrev_b32_e32 v31, 16, v144
	v_and_b32_e32 v32, 0xffff0000, v144
	v_lshlrev_b32_e32 v160, 16, v145
	v_and_b32_e32 v161, 0xffff0000, v145
	v_lshlrev_b32_e32 v162, 16, v146
	v_and_b32_e32 v163, 0xffff0000, v146
	v_lshlrev_b32_e32 v199, 16, v147
	v_and_b32_e32 v200, 0xffff0000, v147
	v_mul_f32_e32 v242, 0x3d372713, v31
	v_mul_f32_e32 v243, 0x3d372713, v32
	v_mul_f32_e32 v244, 0x3d372713, v160
	v_mul_f32_e32 v245, 0x3d372713, v161
	v_mul_f32_e32 v246, 0x3d372713, v162
	v_mul_f32_e32 v247, 0x3d372713, v163
	v_mul_f32_e32 v248, 0x3d372713, v199
	v_mul_f32_e32 v249, 0x3d372713, v200
	v_mul_f32_e32 v242, v242, v31
	v_mul_f32_e32 v243, v243, v32
	v_mul_f32_e32 v244, v244, v160
	v_mul_f32_e32 v245, v245, v161
	v_mul_f32_e32 v246, v246, v162
	v_mul_f32_e32 v247, v247, v163
	v_mul_f32_e32 v248, v248, v199
	v_mul_f32_e32 v249, v249, v200
	v_fma_f32 v242, v242, v31, v31
	v_fma_f32 v243, v243, v32, v32
	v_fma_f32 v244, v244, v160, v160
	v_fma_f32 v245, v245, v161, v161
	v_fma_f32 v246, v246, v162, v162
	v_fma_f32 v247, v247, v163, v163
	v_fma_f32 v248, v248, v199, v199
	v_fma_f32 v249, v249, v200, v200
	v_mul_f32_e32 v242, 0x3fcc422a, v242
	v_mul_f32_e32 v243, 0x3fcc422a, v243
	v_mul_f32_e32 v244, 0x3fcc422a, v244
	v_mul_f32_e32 v245, 0x3fcc422a, v245
	v_mul_f32_e32 v246, 0x3fcc422a, v246
	v_mul_f32_e32 v247, 0x3fcc422a, v247
	v_mul_f32_e32 v248, 0x3fcc422a, v248
	v_mul_f32_e32 v249, 0x3fcc422a, v249
	v_mul_f32_e32 v242, 0xbfb8aa3b, v242
	v_mul_f32_e32 v243, 0xbfb8aa3b, v243
	v_mul_f32_e32 v244, 0xbfb8aa3b, v244
	v_mul_f32_e32 v245, 0xbfb8aa3b, v245
	v_mul_f32_e32 v246, 0xbfb8aa3b, v246
	v_mul_f32_e32 v247, 0xbfb8aa3b, v247
	v_mul_f32_e32 v248, 0xbfb8aa3b, v248
	v_mul_f32_e32 v249, 0xbfb8aa3b, v249
	v_exp_f32_e32 v242, v242
	v_exp_f32_e32 v243, v243
	v_exp_f32_e32 v244, v244
	v_exp_f32_e32 v245, v245
	v_exp_f32_e32 v246, v246
	v_exp_f32_e32 v247, v247
	v_exp_f32_e32 v248, v248
	v_exp_f32_e32 v249, v249
	v_add_f32_e32 v242, 1.0, v242
	v_add_f32_e32 v243, 1.0, v243
	v_add_f32_e32 v244, 1.0, v244
	v_add_f32_e32 v245, 1.0, v245
	v_add_f32_e32 v246, 1.0, v246
	v_add_f32_e32 v247, 1.0, v247
	v_add_f32_e32 v248, 1.0, v248
	v_add_f32_e32 v249, 1.0, v249
	v_rcp_f32_e32 v242, v242
	v_rcp_f32_e32 v243, v243
	v_rcp_f32_e32 v244, v244
	v_rcp_f32_e32 v245, v245
	v_rcp_f32_e32 v246, v246
	v_rcp_f32_e32 v247, v247
	v_rcp_f32_e32 v248, v248
	v_rcp_f32_e32 v249, v249
	v_fma_f32 v19, v242, v31, 0
	v_fmac_f32_e32 v19, v243, v32
	v_fmac_f32_e32 v19, v244, v160
	v_fmac_f32_e32 v19, v245, v161
	v_fmac_f32_e32 v19, v246, v162
	v_fmac_f32_e32 v19, v247, v163
	v_fmac_f32_e32 v19, v248, v199
	v_fmac_f32_e32 v19, v249, v200
	s_waitcnt vmcnt(2)
	v_lshlrev_b32_e32 v31, 16, v148
	v_and_b32_e32 v32, 0xffff0000, v148
	v_lshlrev_b32_e32 v160, 16, v149
	v_and_b32_e32 v161, 0xffff0000, v149
	v_lshlrev_b32_e32 v162, 16, v150
	v_and_b32_e32 v163, 0xffff0000, v150
	v_lshlrev_b32_e32 v199, 16, v151
	v_and_b32_e32 v200, 0xffff0000, v151
	v_mul_f32_e32 v250, 0x3d372713, v31
	v_mul_f32_e32 v251, 0x3d372713, v32
	v_mul_f32_e32 v177, 0x3d372713, v160
	v_mul_f32_e32 v178, 0x3d372713, v161
	v_mul_f32_e32 v179, 0x3d372713, v162
	v_mul_f32_e32 v180, 0x3d372713, v163
	v_mul_f32_e32 v181, 0x3d372713, v199
	v_mul_f32_e32 v182, 0x3d372713, v200
	v_mul_f32_e32 v250, v250, v31
	v_mul_f32_e32 v251, v251, v32
	v_mul_f32_e32 v177, v177, v160
	v_mul_f32_e32 v178, v178, v161
	v_mul_f32_e32 v179, v179, v162
	v_mul_f32_e32 v180, v180, v163
	v_mul_f32_e32 v181, v181, v199
	v_mul_f32_e32 v182, v182, v200
	v_fma_f32 v250, v250, v31, v31
	v_fma_f32 v251, v251, v32, v32
	v_fma_f32 v177, v177, v160, v160
	v_fma_f32 v178, v178, v161, v161
	v_fma_f32 v179, v179, v162, v162
	v_fma_f32 v180, v180, v163, v163
	v_fma_f32 v181, v181, v199, v199
	v_fma_f32 v182, v182, v200, v200
	v_mul_f32_e32 v250, 0x3fcc422a, v250
	v_mul_f32_e32 v251, 0x3fcc422a, v251
	v_mul_f32_e32 v177, 0x3fcc422a, v177
	v_mul_f32_e32 v178, 0x3fcc422a, v178
	v_mul_f32_e32 v179, 0x3fcc422a, v179
	v_mul_f32_e32 v180, 0x3fcc422a, v180
	v_mul_f32_e32 v181, 0x3fcc422a, v181
	v_mul_f32_e32 v182, 0x3fcc422a, v182
	v_mul_f32_e32 v250, 0xbfb8aa3b, v250
	v_mul_f32_e32 v251, 0xbfb8aa3b, v251
	v_mul_f32_e32 v177, 0xbfb8aa3b, v177
	v_mul_f32_e32 v178, 0xbfb8aa3b, v178
	v_mul_f32_e32 v179, 0xbfb8aa3b, v179
	v_mul_f32_e32 v180, 0xbfb8aa3b, v180
	v_mul_f32_e32 v181, 0xbfb8aa3b, v181
	v_mul_f32_e32 v182, 0xbfb8aa3b, v182
	v_exp_f32_e32 v250, v250
	v_exp_f32_e32 v251, v251
	v_exp_f32_e32 v177, v177
	v_exp_f32_e32 v178, v178
	v_exp_f32_e32 v179, v179
	v_exp_f32_e32 v180, v180
	v_exp_f32_e32 v181, v181
	v_exp_f32_e32 v182, v182
	v_add_f32_e32 v250, 1.0, v250
	v_add_f32_e32 v251, 1.0, v251
	v_add_f32_e32 v177, 1.0, v177
	v_add_f32_e32 v178, 1.0, v178
	v_add_f32_e32 v179, 1.0, v179
	v_add_f32_e32 v180, 1.0, v180
	v_add_f32_e32 v181, 1.0, v181
	v_add_f32_e32 v182, 1.0, v182
	v_rcp_f32_e32 v250, v250
	v_rcp_f32_e32 v251, v251
	v_rcp_f32_e32 v177, v177
	v_rcp_f32_e32 v178, v178
	v_rcp_f32_e32 v179, v179
	v_rcp_f32_e32 v180, v180
	v_rcp_f32_e32 v181, v181
	v_rcp_f32_e32 v182, v182
	v_fma_f32 v20, v250, v31, 0
	v_fmac_f32_e32 v20, v251, v32
	v_fmac_f32_e32 v20, v177, v160
	v_fmac_f32_e32 v20, v178, v161
	v_fmac_f32_e32 v20, v179, v162
	v_fmac_f32_e32 v20, v180, v163
	v_fmac_f32_e32 v20, v181, v199
	v_fmac_f32_e32 v20, v182, v200
	s_waitcnt vmcnt(1)
; __device__ __forceinline__ float bf2f(unsigned h) { return __uint_as_float(h << 16); }
; __device__ __forceinline__ float gelu_(float x) { return x * sigm_(1.5957691216f * (x + 0.044715f * x * x * x)); }
; __device__ __forceinline__ float wave_sum(float v) {
; #pragma unroll
;     for (int o = 1; o < 64; o <<= 1) v += __shfl_xor(v, o);
;     return v;
; __device__ __forceinline__ void gmlp_mfma(LAS unsigned char* lds, const unsigned char* R, bf16_t* O, const float* lng, const float* lnb, const float* wsp, const float* bsp, int unit, int tid) {
;     ...
;     for (int i = 0; i < 16; ++i) { const int t = w * 16 + i; const u32x4 x4 = *(const u32x4*)(VV + (r0 + t) * AW + lane * 8);
;         float x[8]; x[0] = gelu_(bf2f(x4.x & 0xffff)); x[1] = gelu_(bf2f(x4.x >> 16)); x[2] = gelu_(bf2f(x4.y & 0xffff)); x[3] = gelu_(bf2f(x4.y >> 16)); x[4] = gelu_(bf2f(x4.z & 0xffff)); x[5] = gelu_(bf2f(x4.z >> 16)); x[6] = gelu_(bf2f(x4.w & 0xffff)); x[7] = gelu_(bf2f(x4.w >> 16));
;         float s = 0.f;
; #pragma unroll
;         for (int j = 0; j < 8; ++j) s += x[j];
;         const float mean = wave_sum(s) * (1.f / 512.f); float q = 0.f;
	v_lshlrev_b32_e32 v31, 16, v152
	v_and_b32_e32 v32, 0xffff0000, v152
	v_lshlrev_b32_e32 v160, 16, v153
	v_and_b32_e32 v161, 0xffff0000, v153
	v_lshlrev_b32_e32 v162, 16, v154
	v_and_b32_e32 v163, 0xffff0000, v154
	v_lshlrev_b32_e32 v199, 16, v155
	v_and_b32_e32 v200, 0xffff0000, v155
	v_mul_f32_e32 v183, 0x3d372713, v31
	v_mul_f32_e32 v184, 0x3d372713, v32
	v_mul_f32_e32 v185, 0x3d372713, v160
	v_mul_f32_e32 v186, 0x3d372713, v161
	v_mul_f32_e32 v187, 0x3d372713, v162
	v_mul_f32_e32 v188, 0x3d372713, v163
	v_mul_f32_e32 v189, 0x3d372713, v199
	v_mul_f32_e32 v190, 0x3d372713, v200
	v_mul_f32_e32 v183, v183, v31
	v_mul_f32_e32 v184, v184, v32
	v_mul_f32_e32 v185, v185, v160
	v_mul_f32_e32 v186, v186, v161
	v_mul_f32_e32 v187, v187, v162
	v_mul_f32_e32 v188, v188, v163
	v_mul_f32_e32 v189, v189, v199
	v_mul_f32_e32 v190, v190, v200
	v_fma_f32 v183, v183, v31, v31
	v_fma_f32 v184, v184, v32, v32
	v_fma_f32 v185, v185, v160, v160
	v_fma_f32 v186, v186, v161, v161
	v_fma_f32 v187, v187, v162, v162
	v_fma_f32 v188, v188, v163, v163
	v_fma_f32 v189, v189, v199, v199
	v_fma_f32 v190, v190, v200, v200
	v_mul_f32_e32 v183, 0x3fcc422a, v183
	v_mul_f32_e32 v184, 0x3fcc422a, v184
	v_mul_f32_e32 v185, 0x3fcc422a, v185
	v_mul_f32_e32 v186, 0x3fcc422a, v186
	v_mul_f32_e32 v187, 0x3fcc422a, v187
	v_mul_f32_e32 v188, 0x3fcc422a, v188
	v_mul_f32_e32 v189, 0x3fcc422a, v189
	v_mul_f32_e32 v190, 0x3fcc422a, v190
	v_mul_f32_e32 v183, 0xbfb8aa3b, v183
	v_mul_f32_e32 v184, 0xbfb8aa3b, v184
	v_mul_f32_e32 v185, 0xbfb8aa3b, v185
	v_mul_f32_e32 v186, 0xbfb8aa3b, v186
	v_mul_f32_e32 v187, 0xbfb8aa3b, v187
	v_mul_f32_e32 v188, 0xbfb8aa3b, v188
	v_mul_f32_e32 v189, 0xbfb8aa3b, v189
	v_mul_f32_e32 v190, 0xbfb8aa3b, v190
	v_exp_f32_e32 v183, v183
	v_exp_f32_e32 v184, v184
	v_exp_f32_e32 v185, v185
	v_exp_f32_e32 v186, v186
	v_exp_f32_e32 v187, v187
	v_exp_f32_e32 v188, v188
	v_exp_f32_e32 v189, v189
	v_exp_f32_e32 v190, v190
	v_add_f32_e32 v183, 1.0, v183
	v_add_f32_e32 v184, 1.0, v184
	v_add_f32_e32 v185, 1.0, v185
	v_add_f32_e32 v186, 1.0, v186
	v_add_f32_e32 v187, 1.0, v187
	v_add_f32_e32 v188, 1.0, v188
	v_add_f32_e32 v189, 1.0, v189
	v_add_f32_e32 v190, 1.0, v190
	v_rcp_f32_e32 v183, v183
	v_rcp_f32_e32 v184, v184
	v_rcp_f32_e32 v185, v185
	v_rcp_f32_e32 v186, v186
	v_rcp_f32_e32 v187, v187
	v_rcp_f32_e32 v188, v188
	v_rcp_f32_e32 v189, v189
	v_rcp_f32_e32 v190, v190
	v_fma_f32 v21, v183, v31, 0
	v_fmac_f32_e32 v21, v184, v32
	v_fmac_f32_e32 v21, v185, v160
	v_fmac_f32_e32 v21, v186, v161
	v_fmac_f32_e32 v21, v187, v162
	v_fmac_f32_e32 v21, v188, v163
	v_fmac_f32_e32 v21, v189, v199
	v_fmac_f32_e32 v21, v190, v200
	s_waitcnt vmcnt(0)
	v_lshlrev_b32_e32 v31, 16, v156
	v_and_b32_e32 v32, 0xffff0000, v156
	v_lshlrev_b32_e32 v160, 16, v157
	v_and_b32_e32 v161, 0xffff0000, v157
	v_lshlrev_b32_e32 v162, 16, v158
	v_and_b32_e32 v163, 0xffff0000, v158
	v_lshlrev_b32_e32 v199, 16, v159
	v_and_b32_e32 v200, 0xffff0000, v159
	v_mul_f32_e32 v191, 0x3d372713, v31
	v_mul_f32_e32 v192, 0x3d372713, v32
	v_mul_f32_e32 v193, 0x3d372713, v160
	v_mul_f32_e32 v194, 0x3d372713, v161
	v_mul_f32_e32 v195, 0x3d372713, v162
	v_mul_f32_e32 v196, 0x3d372713, v163
	v_mul_f32_e32 v197, 0x3d372713, v199
	v_mul_f32_e32 v198, 0x3d372713, v200
	v_mul_f32_e32 v191, v191, v31
	v_mul_f32_e32 v192, v192, v32
	v_mul_f32_e32 v193, v193, v160
	v_mul_f32_e32 v194, v194, v161
	v_mul_f32_e32 v195, v195, v162
	v_mul_f32_e32 v196, v196, v163
	v_mul_f32_e32 v197, v197, v199
	v_mul_f32_e32 v198, v198, v200
	v_fma_f32 v191, v191, v31, v31
	v_fma_f32 v192, v192, v32, v32
	v_fma_f32 v193, v193, v160, v160
	v_fma_f32 v194, v194, v161, v161
	v_fma_f32 v195, v195, v162, v162
	v_fma_f32 v196, v196, v163, v163
	v_fma_f32 v197, v197, v199, v199
	v_fma_f32 v198, v198, v200, v200
	v_mul_f32_e32 v191, 0x3fcc422a, v191
	v_mul_f32_e32 v192, 0x3fcc422a, v192
	v_mul_f32_e32 v193, 0x3fcc422a, v193
	v_mul_f32_e32 v194, 0x3fcc422a, v194
	v_mul_f32_e32 v195, 0x3fcc422a, v195
	v_mul_f32_e32 v196, 0x3fcc422a, v196
	v_mul_f32_e32 v197, 0x3fcc422a, v197
	v_mul_f32_e32 v198, 0x3fcc422a, v198
	v_mul_f32_e32 v191, 0xbfb8aa3b, v191
	v_mul_f32_e32 v192, 0xbfb8aa3b, v192
	v_mul_f32_e32 v193, 0xbfb8aa3b, v193
	v_mul_f32_e32 v194, 0xbfb8aa3b, v194
	v_mul_f32_e32 v195, 0xbfb8aa3b, v195
	v_mul_f32_e32 v196, 0xbfb8aa3b, v196
	v_mul_f32_e32 v197, 0xbfb8aa3b, v197
	v_mul_f32_e32 v198, 0xbfb8aa3b, v198
	v_exp_f32_e32 v191, v191
	v_exp_f32_e32 v192, v192
	v_exp_f32_e32 v193, v193
	v_exp_f32_e32 v194, v194
	v_exp_f32_e32 v195, v195
	v_exp_f32_e32 v196, v196
	v_exp_f32_e32 v197, v197
	v_exp_f32_e32 v198, v198
	v_add_f32_e32 v191, 1.0, v191
	v_add_f32_e32 v192, 1.0, v192
	v_add_f32_e32 v193, 1.0, v193
	v_add_f32_e32 v194, 1.0, v194
	v_add_f32_e32 v195, 1.0, v195
	v_add_f32_e32 v196, 1.0, v196
	v_add_f32_e32 v197, 1.0, v197
	v_add_f32_e32 v198, 1.0, v198
	v_rcp_f32_e32 v191, v191
	v_rcp_f32_e32 v192, v192
	v_rcp_f32_e32 v193, v193
	v_rcp_f32_e32 v194, v194
	v_rcp_f32_e32 v195, v195
	v_rcp_f32_e32 v196, v196
	v_rcp_f32_e32 v197, v197
	v_rcp_f32_e32 v198, v198
	v_fma_f32 v22, v191, v31, 0
	v_fmac_f32_e32 v22, v192, v32
	v_fmac_f32_e32 v22, v193, v160
	v_fmac_f32_e32 v22, v194, v161
	v_fmac_f32_e32 v22, v195, v162
	v_fmac_f32_e32 v22, v196, v163
	v_fmac_f32_e32 v22, v197, v199
	v_fmac_f32_e32 v22, v198, v200
	ds_bpermute_b32 v31, v0, v15
	ds_bpermute_b32 v32, v0, v16
	ds_bpermute_b32 v160, v0, v17
	ds_bpermute_b32 v161, v0, v18
	ds_bpermute_b32 v162, v0, v19
	ds_bpermute_b32 v163, v0, v20
	ds_bpermute_b32 v199, v0, v21
	ds_bpermute_b32 v200, v0, v22
	s_waitcnt lgkmcnt(0)
; __device__ __forceinline__ float wave_sum(float v) {
; #pragma unroll
;     for (int o = 1; o < 64; o <<= 1) v += __shfl_xor(v, o);
;     return v;
; __device__ __forceinline__ void gmlp_mfma(LAS unsigned char* lds, const unsigned char* R, bf16_t* O, const float* lng, const float* lnb, const float* wsp, const float* bsp, int unit, int tid) {
;     ...
;         const float mean = wave_sum(s) * (1.f / 512.f); float q = 0.f;
; #pragma unroll
;         for (int j = 0; j < 8; ++j) q += (x[j] - mean) * (x[j] - mean);
	v_add_f32_e32 v15, v15, v31
	v_add_f32_e32 v16, v16, v32
	v_add_f32_e32 v17, v17, v160
	v_add_f32_e32 v18, v18, v161
	v_add_f32_e32 v19, v19, v162
	v_add_f32_e32 v20, v20, v163
	v_add_f32_e32 v21, v21, v199
	v_add_f32_e32 v22, v22, v200
	ds_bpermute_b32 v31, v10, v15
	ds_bpermute_b32 v32, v10, v16
	ds_bpermute_b32 v160, v10, v17
	ds_bpermute_b32 v161, v10, v18
	ds_bpermute_b32 v162, v10, v19
	ds_bpermute_b32 v163, v10, v20
	ds_bpermute_b32 v199, v10, v21
	ds_bpermute_b32 v200, v10, v22
	s_waitcnt lgkmcnt(0)
	v_add_f32_e32 v15, v15, v31
	v_add_f32_e32 v16, v16, v32
	v_add_f32_e32 v17, v17, v160
	v_add_f32_e32 v18, v18, v161
	v_add_f32_e32 v19, v19, v162
	v_add_f32_e32 v20, v20, v163
	v_add_f32_e32 v21, v21, v199
	v_add_f32_e32 v22, v22, v200
	ds_bpermute_b32 v31, v11, v15
	ds_bpermute_b32 v32, v11, v16
	ds_bpermute_b32 v160, v11, v17
	ds_bpermute_b32 v161, v11, v18
	ds_bpermute_b32 v162, v11, v19
	ds_bpermute_b32 v163, v11, v20
	ds_bpermute_b32 v199, v11, v21
	ds_bpermute_b32 v200, v11, v22
	s_waitcnt lgkmcnt(0)
	v_add_f32_e32 v15, v15, v31
	v_add_f32_e32 v16, v16, v32
	v_add_f32_e32 v17, v17, v160
	v_add_f32_e32 v18, v18, v161
	v_add_f32_e32 v19, v19, v162
	v_add_f32_e32 v20, v20, v163
	v_add_f32_e32 v21, v21, v199
	v_add_f32_e32 v22, v22, v200
	ds_bpermute_b32 v31, v12, v15
	ds_bpermute_b32 v32, v12, v16
	ds_bpermute_b32 v160, v12, v17
	ds_bpermute_b32 v161, v12, v18
	ds_bpermute_b32 v162, v12, v19
	ds_bpermute_b32 v163, v12, v20
	ds_bpermute_b32 v199, v12, v21
	ds_bpermute_b32 v200, v12, v22
	s_waitcnt lgkmcnt(0)
	v_add_f32_e32 v15, v15, v31
	v_add_f32_e32 v16, v16, v32
	v_add_f32_e32 v17, v17, v160
	v_add_f32_e32 v18, v18, v161
	v_add_f32_e32 v19, v19, v162
	v_add_f32_e32 v20, v20, v163
	v_add_f32_e32 v21, v21, v199
	v_add_f32_e32 v22, v22, v200
	ds_bpermute_b32 v31, v13, v15
	ds_bpermute_b32 v32, v13, v16
	ds_bpermute_b32 v160, v13, v17
	ds_bpermute_b32 v161, v13, v18
	ds_bpermute_b32 v162, v13, v19
	ds_bpermute_b32 v163, v13, v20
	ds_bpermute_b32 v199, v13, v21
	ds_bpermute_b32 v200, v13, v22
	s_waitcnt lgkmcnt(0)
	v_add_f32_e32 v15, v15, v31
	v_add_f32_e32 v16, v16, v32
	v_add_f32_e32 v17, v17, v160
	v_add_f32_e32 v18, v18, v161
	v_add_f32_e32 v19, v19, v162
	v_add_f32_e32 v20, v20, v163
	v_add_f32_e32 v21, v21, v199
	v_add_f32_e32 v22, v22, v200
	ds_bpermute_b32 v31, v14, v15
	ds_bpermute_b32 v32, v14, v16
	ds_bpermute_b32 v160, v14, v17
	ds_bpermute_b32 v161, v14, v18
	ds_bpermute_b32 v162, v14, v19
	ds_bpermute_b32 v163, v14, v20
	ds_bpermute_b32 v199, v14, v21
	ds_bpermute_b32 v200, v14, v22
	s_waitcnt lgkmcnt(0)
	v_add_f32_e32 v15, v15, v31
	v_add_f32_e32 v16, v16, v32
	v_add_f32_e32 v17, v17, v160
	v_add_f32_e32 v18, v18, v161
	v_add_f32_e32 v19, v19, v162
	v_add_f32_e32 v20, v20, v163
	v_add_f32_e32 v21, v21, v199
	v_add_f32_e32 v22, v22, v200
	v_mul_f32_e32 v15, 0x3b000000, v15
	v_mul_f32_e32 v16, 0x3b000000, v16
	v_mul_f32_e32 v17, 0x3b000000, v17
	v_mul_f32_e32 v18, 0x3b000000, v18
	v_mul_f32_e32 v19, 0x3b000000, v19
	v_mul_f32_e32 v20, 0x3b000000, v20
	v_mul_f32_e32 v21, 0x3b000000, v21
	v_mul_f32_e32 v22, 0x3b000000, v22
	v_lshlrev_b32_e32 v31, 16, v128
	v_and_b32_e32 v32, 0xffff0000, v128
	v_lshlrev_b32_e32 v160, 16, v129
	v_and_b32_e32 v161, 0xffff0000, v129
	v_lshlrev_b32_e32 v162, 16, v130
	v_and_b32_e32 v163, 0xffff0000, v130
	v_lshlrev_b32_e32 v199, 16, v131
	v_and_b32_e32 v200, 0xffff0000, v131
	v_fma_f32 v31, v210, v31, -v15
	v_fma_f32 v32, v211, v32, -v15
	v_fma_f32 v160, v212, v160, -v15
	v_fma_f32 v161, v213, v161, -v15
	v_fma_f32 v162, v214, v162, -v15
	v_fma_f32 v163, v215, v163, -v15
	v_fma_f32 v199, v216, v199, -v15
	v_fma_f32 v200, v217, v200, -v15
	v_mul_f32_e32 v23, v32, v32
	v_fmac_f32_e32 v23, v31, v31
	v_fmac_f32_e32 v23, v160, v160
	v_fmac_f32_e32 v23, v161, v161
	v_fmac_f32_e32 v23, v162, v162
	v_fmac_f32_e32 v23, v163, v163
	v_fmac_f32_e32 v23, v199, v199
	v_fmac_f32_e32 v23, v200, v200
	v_lshlrev_b32_e32 v31, 16, v132
	v_and_b32_e32 v32, 0xffff0000, v132
	v_lshlrev_b32_e32 v160, 16, v133
	v_and_b32_e32 v161, 0xffff0000, v133
	v_lshlrev_b32_e32 v162, 16, v134
	v_and_b32_e32 v163, 0xffff0000, v134
	v_lshlrev_b32_e32 v199, 16, v135
	v_and_b32_e32 v200, 0xffff0000, v135
	v_fma_f32 v31, v218, v31, -v16
	v_fma_f32 v32, v219, v32, -v16
	v_fma_f32 v160, v220, v160, -v16
	v_fma_f32 v161, v221, v161, -v16
	v_fma_f32 v162, v222, v162, -v16
	v_fma_f32 v163, v223, v163, -v16
	v_fma_f32 v199, v224, v199, -v16
	v_fma_f32 v200, v225, v200, -v16
	v_mul_f32_e32 v24, v32, v32
	v_fmac_f32_e32 v24, v31, v31
	v_fmac_f32_e32 v24, v160, v160
	v_fmac_f32_e32 v24, v161, v161
	v_fmac_f32_e32 v24, v162, v162
	v_fmac_f32_e32 v24, v163, v163
	v_fmac_f32_e32 v24, v199, v199
	v_fmac_f32_e32 v24, v200, v200
	v_lshlrev_b32_e32 v31, 16, v136
	v_and_b32_e32 v32, 0xffff0000, v136
	v_lshlrev_b32_e32 v160, 16, v137
	v_and_b32_e32 v161, 0xffff0000, v137
	v_lshlrev_b32_e32 v162, 16, v138
	v_and_b32_e32 v163, 0xffff0000, v138
	v_lshlrev_b32_e32 v199, 16, v139
	v_and_b32_e32 v200, 0xffff0000, v139
	v_fma_f32 v31, v226, v31, -v17
	v_fma_f32 v32, v227, v32, -v17
	v_fma_f32 v160, v228, v160, -v17
	v_fma_f32 v161, v229, v161, -v17
	v_fma_f32 v162, v230, v162, -v17
	v_fma_f32 v163, v231, v163, -v17
	v_fma_f32 v199, v232, v199, -v17
	v_fma_f32 v200, v233, v200, -v17
	v_mul_f32_e32 v25, v32, v32
	v_fmac_f32_e32 v25, v31, v31
	v_fmac_f32_e32 v25, v160, v160
	v_fmac_f32_e32 v25, v161, v161
	v_fmac_f32_e32 v25, v162, v162
	v_fmac_f32_e32 v25, v163, v163
	v_fmac_f32_e32 v25, v199, v199
	v_fmac_f32_e32 v25, v200, v200
	v_lshlrev_b32_e32 v31, 16, v140
	v_and_b32_e32 v32, 0xffff0000, v140
	v_lshlrev_b32_e32 v160, 16, v141
	v_and_b32_e32 v161, 0xffff0000, v141
; __device__ __forceinline__ float wave_sum(float v) {
; #pragma unroll
;     for (int o = 1; o < 64; o <<= 1) v += __shfl_xor(v, o);
;     return v;
; __device__ __forceinline__ void gmlp_mfma(LAS unsigned char* lds, const unsigned char* R, bf16_t* O, const float* lng, const float* lnb, const float* wsp, const float* bsp, int unit, int tid) {
;     ...
;         for (int j = 0; j < 8; ++j) q += (x[j] - mean) * (x[j] - mean);
;         const float rstd = rsqrtf(wave_sum(q) * (1.f / 512.f) + EPS);
	v_lshlrev_b32_e32 v162, 16, v142
	v_and_b32_e32 v163, 0xffff0000, v142
	v_lshlrev_b32_e32 v199, 16, v143
	v_and_b32_e32 v200, 0xffff0000, v143
	v_fma_f32 v31, v234, v31, -v18
	v_fma_f32 v32, v235, v32, -v18
	v_fma_f32 v160, v236, v160, -v18
	v_fma_f32 v161, v237, v161, -v18
	v_fma_f32 v162, v238, v162, -v18
	v_fma_f32 v163, v239, v163, -v18
	v_fma_f32 v199, v240, v199, -v18
	v_fma_f32 v200, v241, v200, -v18
	v_mul_f32_e32 v26, v32, v32
	v_fmac_f32_e32 v26, v31, v31
	v_fmac_f32_e32 v26, v160, v160
	v_fmac_f32_e32 v26, v161, v161
	v_fmac_f32_e32 v26, v162, v162
	v_fmac_f32_e32 v26, v163, v163
	v_fmac_f32_e32 v26, v199, v199
	v_fmac_f32_e32 v26, v200, v200
	v_lshlrev_b32_e32 v31, 16, v144
	v_and_b32_e32 v32, 0xffff0000, v144
	v_lshlrev_b32_e32 v160, 16, v145
	v_and_b32_e32 v161, 0xffff0000, v145
	v_lshlrev_b32_e32 v162, 16, v146
	v_and_b32_e32 v163, 0xffff0000, v146
	v_lshlrev_b32_e32 v199, 16, v147
	v_and_b32_e32 v200, 0xffff0000, v147
	v_fma_f32 v31, v242, v31, -v19
	v_fma_f32 v32, v243, v32, -v19
	v_fma_f32 v160, v244, v160, -v19
	v_fma_f32 v161, v245, v161, -v19
	v_fma_f32 v162, v246, v162, -v19
	v_fma_f32 v163, v247, v163, -v19
	v_fma_f32 v199, v248, v199, -v19
	v_fma_f32 v200, v249, v200, -v19
	v_mul_f32_e32 v27, v32, v32
	v_fmac_f32_e32 v27, v31, v31
	v_fmac_f32_e32 v27, v160, v160
	v_fmac_f32_e32 v27, v161, v161
	v_fmac_f32_e32 v27, v162, v162
	v_fmac_f32_e32 v27, v163, v163
	v_fmac_f32_e32 v27, v199, v199
	v_fmac_f32_e32 v27, v200, v200
	v_lshlrev_b32_e32 v31, 16, v148
	v_and_b32_e32 v32, 0xffff0000, v148
	v_lshlrev_b32_e32 v160, 16, v149
	v_and_b32_e32 v161, 0xffff0000, v149
	v_lshlrev_b32_e32 v162, 16, v150
	v_and_b32_e32 v163, 0xffff0000, v150
	v_lshlrev_b32_e32 v199, 16, v151
	v_and_b32_e32 v200, 0xffff0000, v151
	v_fma_f32 v31, v250, v31, -v20
	v_fma_f32 v32, v251, v32, -v20
	v_fma_f32 v160, v177, v160, -v20
	v_fma_f32 v161, v178, v161, -v20
	v_fma_f32 v162, v179, v162, -v20
	v_fma_f32 v163, v180, v163, -v20
	v_fma_f32 v199, v181, v199, -v20
	v_fma_f32 v200, v182, v200, -v20
	v_mul_f32_e32 v28, v32, v32
	v_fmac_f32_e32 v28, v31, v31
	v_fmac_f32_e32 v28, v160, v160
	v_fmac_f32_e32 v28, v161, v161
	v_fmac_f32_e32 v28, v162, v162
	v_fmac_f32_e32 v28, v163, v163
	v_fmac_f32_e32 v28, v199, v199
	v_fmac_f32_e32 v28, v200, v200
	v_lshlrev_b32_e32 v31, 16, v152
	v_and_b32_e32 v32, 0xffff0000, v152
	v_lshlrev_b32_e32 v160, 16, v153
	v_and_b32_e32 v161, 0xffff0000, v153
	v_lshlrev_b32_e32 v162, 16, v154
	v_and_b32_e32 v163, 0xffff0000, v154
	v_lshlrev_b32_e32 v199, 16, v155
	v_and_b32_e32 v200, 0xffff0000, v155
	v_fma_f32 v31, v183, v31, -v21
	v_fma_f32 v32, v184, v32, -v21
	v_fma_f32 v160, v185, v160, -v21
	v_fma_f32 v161, v186, v161, -v21
	v_fma_f32 v162, v187, v162, -v21
	v_fma_f32 v163, v188, v163, -v21
	v_fma_f32 v199, v189, v199, -v21
	v_fma_f32 v200, v190, v200, -v21
	v_mul_f32_e32 v29, v32, v32
	v_fmac_f32_e32 v29, v31, v31
	v_fmac_f32_e32 v29, v160, v160
	v_fmac_f32_e32 v29, v161, v161
	v_fmac_f32_e32 v29, v162, v162
	v_fmac_f32_e32 v29, v163, v163
	v_fmac_f32_e32 v29, v199, v199
	v_fmac_f32_e32 v29, v200, v200
	v_lshlrev_b32_e32 v31, 16, v156
	v_and_b32_e32 v32, 0xffff0000, v156
	v_lshlrev_b32_e32 v160, 16, v157
	v_and_b32_e32 v161, 0xffff0000, v157
	v_lshlrev_b32_e32 v162, 16, v158
	v_and_b32_e32 v163, 0xffff0000, v158
	v_lshlrev_b32_e32 v199, 16, v159
	v_and_b32_e32 v200, 0xffff0000, v159
	v_fma_f32 v31, v191, v31, -v22
	v_fma_f32 v32, v192, v32, -v22
	v_fma_f32 v160, v193, v160, -v22
	v_fma_f32 v161, v194, v161, -v22
	v_fma_f32 v162, v195, v162, -v22
	v_fma_f32 v163, v196, v163, -v22
	v_fma_f32 v199, v197, v199, -v22
	v_fma_f32 v200, v198, v200, -v22
	v_mul_f32_e32 v30, v32, v32
	v_fmac_f32_e32 v30, v31, v31
	v_fmac_f32_e32 v30, v160, v160
	v_fmac_f32_e32 v30, v161, v161
	v_fmac_f32_e32 v30, v162, v162
	v_fmac_f32_e32 v30, v163, v163
	v_fmac_f32_e32 v30, v199, v199
	v_fmac_f32_e32 v30, v200, v200
	ds_bpermute_b32 v31, v0, v23
	ds_bpermute_b32 v32, v0, v24
	ds_bpermute_b32 v160, v0, v25
	ds_bpermute_b32 v161, v0, v26
	ds_bpermute_b32 v162, v0, v27
	ds_bpermute_b32 v163, v0, v28
	ds_bpermute_b32 v199, v0, v29
	ds_bpermute_b32 v200, v0, v30
	s_waitcnt lgkmcnt(0)
	v_add_f32_e32 v23, v23, v31
	v_add_f32_e32 v24, v24, v32
	v_add_f32_e32 v25, v25, v160
	v_add_f32_e32 v26, v26, v161
	v_add_f32_e32 v27, v27, v162
	v_add_f32_e32 v28, v28, v163
	v_add_f32_e32 v29, v29, v199
	v_add_f32_e32 v30, v30, v200
	ds_bpermute_b32 v31, v10, v23
	ds_bpermute_b32 v32, v10, v24
	ds_bpermute_b32 v160, v10, v25
	ds_bpermute_b32 v161, v10, v26
	ds_bpermute_b32 v162, v10, v27
	ds_bpermute_b32 v163, v10, v28
	ds_bpermute_b32 v199, v10, v29
	ds_bpermute_b32 v200, v10, v30
	s_waitcnt lgkmcnt(0)
; __device__ __forceinline__ float wave_sum(float v) {
; #pragma unroll
;     for (int o = 1; o < 64; o <<= 1) v += __shfl_xor(v, o);
;     return v;
; __device__ __forceinline__ void gmlp_mfma(LAS unsigned char* lds, const unsigned char* R, bf16_t* O, const float* lng, const float* lnb, const float* wsp, const float* bsp, int unit, int tid) {
;     ...
;         for (int j = 0; j < 8; ++j) q += (x[j] - mean) * (x[j] - mean);
;         const float rstd = rsqrtf(wave_sum(q) * (1.f / 512.f) + EPS);
;         if (lane == 0) { mu[t] = mean; rs[t] = rstd; } }
	v_add_f32_e32 v23, v23, v31
	v_add_f32_e32 v24, v24, v32
	v_add_f32_e32 v25, v25, v160
	v_add_f32_e32 v26, v26, v161
	v_add_f32_e32 v27, v27, v162
	v_add_f32_e32 v28, v28, v163
	v_add_f32_e32 v29, v29, v199
	v_add_f32_e32 v30, v30, v200
	ds_bpermute_b32 v31, v11, v23
	ds_bpermute_b32 v32, v11, v24
	ds_bpermute_b32 v160, v11, v25
	ds_bpermute_b32 v161, v11, v26
	ds_bpermute_b32 v162, v11, v27
	ds_bpermute_b32 v163, v11, v28
	ds_bpermute_b32 v199, v11, v29
	ds_bpermute_b32 v200, v11, v30
	s_waitcnt lgkmcnt(0)
	v_add_f32_e32 v23, v23, v31
	v_add_f32_e32 v24, v24, v32
	v_add_f32_e32 v25, v25, v160
	v_add_f32_e32 v26, v26, v161
	v_add_f32_e32 v27, v27, v162
	v_add_f32_e32 v28, v28, v163
	v_add_f32_e32 v29, v29, v199
	v_add_f32_e32 v30, v30, v200
	ds_bpermute_b32 v31, v12, v23
	ds_bpermute_b32 v32, v12, v24
	ds_bpermute_b32 v160, v12, v25
	ds_bpermute_b32 v161, v12, v26
	ds_bpermute_b32 v162, v12, v27
	ds_bpermute_b32 v163, v12, v28
	ds_bpermute_b32 v199, v12, v29
	ds_bpermute_b32 v200, v12, v30
	s_waitcnt lgkmcnt(0)
	v_add_f32_e32 v23, v23, v31
	v_add_f32_e32 v24, v24, v32
	v_add_f32_e32 v25, v25, v160
	v_add_f32_e32 v26, v26, v161
	v_add_f32_e32 v27, v27, v162
	v_add_f32_e32 v28, v28, v163
	v_add_f32_e32 v29, v29, v199
	v_add_f32_e32 v30, v30, v200
	ds_bpermute_b32 v31, v13, v23
	ds_bpermute_b32 v32, v13, v24
	ds_bpermute_b32 v160, v13, v25
	ds_bpermute_b32 v161, v13, v26
	ds_bpermute_b32 v162, v13, v27
	ds_bpermute_b32 v163, v13, v28
	ds_bpermute_b32 v199, v13, v29
	ds_bpermute_b32 v200, v13, v30
	s_waitcnt lgkmcnt(0)
	v_add_f32_e32 v23, v23, v31
	v_add_f32_e32 v24, v24, v32
	v_add_f32_e32 v25, v25, v160
	v_add_f32_e32 v26, v26, v161
	v_add_f32_e32 v27, v27, v162
	v_add_f32_e32 v28, v28, v163
	v_add_f32_e32 v29, v29, v199
	v_add_f32_e32 v30, v30, v200
	ds_bpermute_b32 v31, v14, v23
	ds_bpermute_b32 v32, v14, v24
	ds_bpermute_b32 v160, v14, v25
	ds_bpermute_b32 v161, v14, v26
	ds_bpermute_b32 v162, v14, v27
	ds_bpermute_b32 v163, v14, v28
	ds_bpermute_b32 v199, v14, v29
	ds_bpermute_b32 v200, v14, v30
	s_waitcnt lgkmcnt(0)
	v_add_f32_e32 v23, v23, v31
	v_add_f32_e32 v24, v24, v32
	v_add_f32_e32 v25, v25, v160
	v_add_f32_e32 v26, v26, v161
	v_add_f32_e32 v27, v27, v162
	v_add_f32_e32 v28, v28, v163
	v_add_f32_e32 v29, v29, v199
	v_add_f32_e32 v30, v30, v200
	v_fmamk_f32 v23, v23, 0x3b000000, v204
	v_fmamk_f32 v24, v24, 0x3b000000, v204
	v_fmamk_f32 v25, v25, 0x3b000000, v204
	v_fmamk_f32 v26, v26, 0x3b000000, v204
	v_fmamk_f32 v27, v27, 0x3b000000, v204
	v_fmamk_f32 v28, v28, 0x3b000000, v204
	v_fmamk_f32 v29, v29, 0x3b000000, v204
	v_fmamk_f32 v30, v30, 0x3b000000, v204
	v_cmp_gt_f32_e32 vcc, s24, v23
	v_mul_f32_e32 v31, 0x4b800000, v23
	s_nop 0
	v_cndmask_b32_e32 v23, v23, v31, vcc
	v_rsq_f32_e32 v23, v23
	s_nop 0
	v_mul_f32_e32 v31, 0x45800000, v23
	v_cndmask_b32_e32 v23, v23, v31, vcc
	v_cmp_gt_f32_e32 vcc, s24, v24
	v_mul_f32_e32 v31, 0x4b800000, v24
	s_nop 0
	v_cndmask_b32_e32 v24, v24, v31, vcc
	v_rsq_f32_e32 v24, v24
	s_nop 0
	v_mul_f32_e32 v31, 0x45800000, v24
	v_cndmask_b32_e32 v24, v24, v31, vcc
	v_cmp_gt_f32_e32 vcc, s24, v25
	v_mul_f32_e32 v31, 0x4b800000, v25
	s_nop 0
	v_cndmask_b32_e32 v25, v25, v31, vcc
	v_rsq_f32_e32 v25, v25
	s_nop 0
	v_mul_f32_e32 v31, 0x45800000, v25
	v_cndmask_b32_e32 v25, v25, v31, vcc
	v_cmp_gt_f32_e32 vcc, s24, v26
	v_mul_f32_e32 v31, 0x4b800000, v26
	s_nop 0
	v_cndmask_b32_e32 v26, v26, v31, vcc
	v_rsq_f32_e32 v26, v26
	s_nop 0
	v_mul_f32_e32 v31, 0x45800000, v26
	v_cndmask_b32_e32 v26, v26, v31, vcc
	v_cmp_gt_f32_e32 vcc, s24, v27
	v_mul_f32_e32 v31, 0x4b800000, v27
	s_nop 0
	v_cndmask_b32_e32 v27, v27, v31, vcc
	v_rsq_f32_e32 v27, v27
	s_nop 0
	v_mul_f32_e32 v31, 0x45800000, v27
	v_cndmask_b32_e32 v27, v27, v31, vcc
	v_cmp_gt_f32_e32 vcc, s24, v28
	v_mul_f32_e32 v31, 0x4b800000, v28
	s_nop 0
	v_cndmask_b32_e32 v28, v28, v31, vcc
	v_rsq_f32_e32 v28, v28
	s_nop 0
	v_mul_f32_e32 v31, 0x45800000, v28
	v_cndmask_b32_e32 v28, v28, v31, vcc
	v_cmp_gt_f32_e32 vcc, s24, v29
	v_mul_f32_e32 v31, 0x4b800000, v29
	s_nop 0
	v_cndmask_b32_e32 v29, v29, v31, vcc
	v_rsq_f32_e32 v29, v29
	s_nop 0
	v_mul_f32_e32 v31, 0x45800000, v29
	v_cndmask_b32_e32 v29, v29, v31, vcc
	v_cmp_gt_f32_e32 vcc, s24, v30
	v_mul_f32_e32 v31, 0x4b800000, v30
	s_nop 0
	v_cndmask_b32_e32 v30, v30, v31, vcc
	v_rsq_f32_e32 v30, v30
	s_nop 0
	v_mul_f32_e32 v31, 0x45800000, v30
	v_cndmask_b32_e32 v30, v30, v31, vcc
	v_mov_b32_e32 v32, s19
	v_add_u32_e32 v32, 0x11000, v32
	s_and_saveexec_b64 s[14:15], s[42:43]
	ds_write_b32 v32, v15 offset:32
	ds_write_b32 v32, v23 offset:544
	ds_write_b32 v32, v16 offset:36
	ds_write_b32 v32, v24 offset:548
	ds_write_b32 v32, v17 offset:40
	ds_write_b32 v32, v25 offset:552
	ds_write_b32 v32, v18 offset:44
	ds_write_b32 v32, v26 offset:556
	ds_write_b32 v32, v19 offset:48
	ds_write_b32 v32, v27 offset:560
	ds_write_b32 v32, v20 offset:52
	ds_write_b32 v32, v28 offset:564
	ds_write_b32 v32, v21 offset:56
	ds_write_b32 v32, v29 offset:568
	ds_write_b32 v32, v22 offset:60
	ds_write_b32 v32, v30 offset:572
	s_or_b64 exec, exec, s[14:15]
	s_mov_b64 s[14:15], 0x400
